# GEMM K-loops: per-segment s_setprio toggles removed, trailing wave half runs the loop at static priority 1
# speedup vs baseline: 1.0174x; 1.0065x over previous
;     __device__ __forceinline__ const char* a_ptr(const Gemm& g, const Unit& u, size_t tsA) const { return (const char*)g.A + (size_t)u.pm * tsA + (size_t)u.pn * g.a_pn_bytes + (u.ks > 0 ? (size_t)u.ks * g.ks_bytes : 0); }
;     __device__ __forceinline__ const char* b_ptr(const Gemm& g, const Unit& u, size_t tsB) const { return (const char*)g.Bt + (size_t)u.pn * tsB + (u.ks > 0 ? (size_t)u.ks * g.ks_bytes : 0); }
;     __device__ __forceinline__ const char* a_ptr(const Gemm& g, const Unit& u, size_t tsA) const { return (const char*)g.A + (size_t)u.pm * tsA + (size_t)u.pn * g.a_pn_bytes + (u.ks > 0 ? (size_t)u.ks * g.ks_bytes : 0); }
;     __device__ __forceinline__ const char* b_ptr(const Gemm& g, const Unit& u, size_t tsB) const { return (const char*)g.Bt + (size_t)u.pn * tsB + (u.ks > 0 ? (size_t)u.ks * g.ks_bytes : 0); }
; #define PG8_WAIT_V(n) asm volatile("s_waitcnt vmcnt(" #n ")" ::: "memory")
; template <class Epi, class Sched, bool ALIGN_EPI = false, bool SP2 = false>
; __device__ __forceinline__ void gemm_phase(PG8_LAS unsigned char* lds, const Gemm g, const Sched& S, const Epi& E, const int wid) {
;     ...
;         const bool has_next = S.next(ui + 1, nxt);
;         const char* nA = has_next ? S.a_ptr(g, nxt, tsA) : cA; const char* nB = has_next ? S.b_ptr(g, nxt, tsB) : cB;
;         const int nt = cur.ks >= 0 ? g.nt_split : ntfull;
; #pragma unroll 1
;         for (int t = 0; t < nt; t += 2) {
;             const bool last = (t == nt - 2);
;             const char* a1 = cA + (size_t)(t + 1) * kstep;
;             const char* a2 = last ? nA : cA + (size_t)(t + 2) * kstep; const char* b2 = last ? nB : cB + (size_t)(t + 2) * kstep;
;             const char* a3 = a2 + kstep; const char* b3 = b2 + kstep;
;             if (last && has_next) S.a_ready(nxt);
;             if constexpr (SP2) {
;             PG8_LDB(B0, 0, 0); PG8_LDB(B1, 0, 1); PG8_SCHED; PG8_LDA(At, 0, 0); PG8_STAGE(PG8_SA(1, 1), a1 + hsA, voffA);
;             PG8_WAIT_V(8); PG8_WAIT_L(0); PG8_BAR; PG8_MMA(0, 0, At, B0); PG8_MMA(0, 1, At, B1); PG8_BAR; PG8_SCHED;
;     ...
; #pragma unroll
;         for (int a = 0; a < 2; ++a)
; #pragma unroll
;             for (int b = 0; b < 2; ++b)
; #pragma unroll
;                 for (int m = 0; m < 4; ++m)
; #pragma unroll
;                     for (int n = 0; n < 2; ++n) acc[a][b][m][n] = (f32x4){0.f, 0.f, 0.f, 0.f};
.LBB0_235:
	s_ashr_i32 s65, s64, 31
	s_lshl_b64 s[24:25], s[64:65], 19
	s_add_u32 s66, s13, s24
	s_addc_u32 s67, s31, s25
	s_and_b64 s[24:25], s[4:5], exec
	s_cselect_b32 s3, s67, s9
	s_cselect_b32 s7, s66, s8
	s_ashr_i32 s63, s62, 31
	s_lshl_b64 s[24:25], s[62:63], 19
	s_add_u32 s68, s35, s24
	s_addc_u32 s69, s77, s25
	s_and_b64 s[24:25], s[4:5], exec
	s_cselect_b32 s26, s69, s73
	s_cselect_b32 s27, s68, s72
	s_add_u32 s8, s8, 0x40080
	s_addc_u32 s9, s9, 0
	s_add_u32 s34, s72, 0x100
	v_mov_b32_e32 v2, 0
	s_addc_u32 s63, s73, 0
	s_mov_b32 s65, -2
	v_mov_b32_e32 v3, v2
	v_mov_b32_e32 v4, v2
	v_mov_b32_e32 v5, v2
	v_mov_b32_e32 v6, v2
	v_mov_b32_e32 v7, v2
	v_mov_b32_e32 v8, v2
	v_mov_b32_e32 v9, v2
	v_mov_b32_e32 v18, v2
	v_mov_b32_e32 v19, v2
	v_mov_b32_e32 v20, v2
	v_mov_b32_e32 v21, v2
	v_mov_b32_e32 v22, v2
	v_mov_b32_e32 v23, v2
	v_mov_b32_e32 v24, v2
	v_mov_b32_e32 v25, v2
	v_mov_b32_e32 v34, v2
	v_mov_b32_e32 v35, v2
	v_mov_b32_e32 v36, v2
	v_mov_b32_e32 v37, v2
	v_mov_b32_e32 v38, v2
	v_mov_b32_e32 v39, v2
	v_mov_b32_e32 v40, v2
	v_mov_b32_e32 v41, v2
	v_mov_b32_e32 v50, v2
	v_mov_b32_e32 v51, v2
	v_mov_b32_e32 v52, v2
	v_mov_b32_e32 v53, v2
	v_mov_b32_e32 v54, v2
	v_mov_b32_e32 v55, v2
	v_mov_b32_e32 v56, v2
	v_mov_b32_e32 v57, v2
	v_mov_b32_e32 v10, v2
	v_mov_b32_e32 v11, v2
	v_mov_b32_e32 v12, v2
	v_mov_b32_e32 v13, v2
	v_mov_b32_e32 v14, v2
	v_mov_b32_e32 v15, v2
	v_mov_b32_e32 v16, v2
	v_mov_b32_e32 v17, v2
	v_mov_b32_e32 v26, v2
	v_mov_b32_e32 v27, v2
	v_mov_b32_e32 v28, v2
	v_mov_b32_e32 v29, v2
	v_mov_b32_e32 v30, v2
	v_mov_b32_e32 v31, v2
	v_mov_b32_e32 v32, v2
	v_mov_b32_e32 v33, v2
	v_mov_b32_e32 v42, v2
	v_mov_b32_e32 v43, v2
	v_mov_b32_e32 v44, v2
	v_mov_b32_e32 v45, v2
	v_mov_b32_e32 v46, v2
	v_mov_b32_e32 v47, v2
	v_mov_b32_e32 v48, v2
	v_mov_b32_e32 v49, v2
	v_mov_b32_e32 v58, v2
	v_mov_b32_e32 v59, v2
	v_mov_b32_e32 v60, v2
	v_mov_b32_e32 v61, v2
	v_mov_b32_e32 v62, v2
	v_mov_b32_e32 v63, v2
	v_mov_b32_e32 v64, v2
	v_mov_b32_e32 v65, v2
	v_mov_b32_e32 v66, v2
	v_mov_b32_e32 v67, v2
	v_mov_b32_e32 v68, v2
	v_mov_b32_e32 v69, v2
	v_mov_b32_e32 v70, v2
	v_mov_b32_e32 v71, v2
	v_mov_b32_e32 v72, v2
	v_mov_b32_e32 v73, v2
	v_mov_b32_e32 v82, v2
	v_mov_b32_e32 v83, v2
	v_mov_b32_e32 v84, v2
	v_mov_b32_e32 v85, v2
	v_mov_b32_e32 v86, v2
	v_mov_b32_e32 v87, v2
	v_mov_b32_e32 v88, v2
	v_mov_b32_e32 v89, v2
	v_mov_b32_e32 v98, v2
	v_mov_b32_e32 v99, v2
	v_mov_b32_e32 v100, v2
	v_mov_b32_e32 v101, v2
	v_mov_b32_e32 v102, v2
	v_mov_b32_e32 v103, v2
	v_mov_b32_e32 v104, v2
	v_mov_b32_e32 v105, v2
	v_mov_b32_e32 v114, v2
	v_mov_b32_e32 v115, v2
	v_mov_b32_e32 v116, v2
	v_mov_b32_e32 v117, v2
	v_mov_b32_e32 v118, v2
	v_mov_b32_e32 v119, v2
	v_mov_b32_e32 v120, v2
	v_mov_b32_e32 v121, v2
	v_mov_b32_e32 v74, v2
	v_mov_b32_e32 v75, v2
	v_mov_b32_e32 v76, v2
	v_mov_b32_e32 v77, v2
	v_mov_b32_e32 v78, v2
	v_mov_b32_e32 v79, v2
	v_mov_b32_e32 v80, v2
	v_mov_b32_e32 v81, v2
	v_mov_b32_e32 v90, v2
	v_mov_b32_e32 v91, v2
	v_mov_b32_e32 v92, v2
	v_mov_b32_e32 v93, v2
	v_mov_b32_e32 v94, v2
	v_mov_b32_e32 v95, v2
	v_mov_b32_e32 v96, v2
	v_mov_b32_e32 v97, v2
	v_mov_b32_e32 v106, v2
	v_mov_b32_e32 v107, v2
	v_mov_b32_e32 v108, v2
	v_mov_b32_e32 v109, v2
	v_mov_b32_e32 v110, v2
	v_mov_b32_e32 v111, v2
	v_mov_b32_e32 v112, v2
	v_mov_b32_e32 v113, v2
	v_mov_b32_e32 v122, v2
	v_mov_b32_e32 v123, v2
	v_mov_b32_e32 v124, v2
	v_mov_b32_e32 v125, v2
	v_mov_b32_e32 v126, v2
	v_mov_b32_e32 v127, v2
	v_mov_b32_e32 v128, v2
	v_mov_b32_e32 v129, v2
	s_cmp_lg_u64 s[46:47], 0
	s_cbranch_scc1 .Lsprio0
	s_setprio 1
.Lsprio0:
.LBB0_236:
	ds_read_b128 v[130:133], v175
	ds_read_b128 v[134:137], v175 offset:1024
	ds_read_b128 v[138:141], v175 offset:2048
	ds_read_b128 v[142:145], v175 offset:3072
	ds_read_b128 v[146:149], v176
	ds_read_b128 v[164:167], v176 offset:1024
	ds_read_b128 v[168:171], v176 offset:2048
	ds_read_b128 v[182:185], v176 offset:3072
	s_add_u32 s24, s8, 0xfffc0080
	s_addc_u32 s25, s9, -1
	s_cmp_eq_u32 s65, 12
	s_cselect_b32 s75, s3, s25
	s_cselect_b32 s74, s7, s24
	s_cselect_b32 s73, s26, s63
	s_cselect_b32 s72, s27, s34
	v_lshl_add_u64 v[172:173], s[8:9], 0, v[156:157]
	s_add_i32 m0, s71, 0xc000
	ds_read_b128 v[186:189], v177
	ds_read_b128 v[190:193], v177 offset:1024
	ds_read_b128 v[194:197], v177 offset:2048
	ds_read_b128 v[198:201], v177 offset:3072
	ds_read_b128 v[202:205], v177 offset:4096
	ds_read_b128 v[206:209], v177 offset:5120
	ds_read_b128 v[210:213], v177 offset:6144
	ds_read_b128 v[214:217], v177 offset:7168
	global_load_lds_dwordx4 v[172:173], off
	v_lshl_add_u64 v[172:173], s[8:9], 0, v[158:159]
	s_add_i32 m0, s71, 0xe000
	s_nop 0
	global_load_lds_dwordx4 v[172:173], off
	s_waitcnt vmcnt(8)
	s_waitcnt lgkmcnt(0)
	s_barrier
; #define PG8_STAGE(bufoff, gbase, voff) do { _Pragma("unroll") for (int _i = 0; _i < 2; ++_i) \
;         __builtin_amdgcn_global_load_lds((const unsigned*)((const char*)(gbase) + (voff)[_i]), (PG8_LAS unsigned*)(lds + (bufoff) + ldsw + _i * 8192), 16, 0, 0); } while (0)
; #define PG8_LDA(dst, b, h) do { _Pragma("unroll") for (int m = 0; m < 4; ++m) _Pragma("unroll") for (int k = 0; k < 2; ++k) dst[m][k] = *(const PG8_LAS bf16x8*)(lds + PG8_SA(b, h) + aoff + m * 2048 + k * 1024); } while (0)
; #define PG8_MMA(ai, bj, At, Bt) do { __builtin_amdgcn_s_setprio(1); _Pragma("unroll") for (int m = 0; m < 4; ++m) _Pragma("unroll") for (int n = 0; n < 2; ++n) _Pragma("unroll") for (int k = 0; k < 2; ++k) \
;         acc[ai][bj][m][n] = __builtin_amdgcn_mfma_f32_16x16x32_bf16(Bt[n][k], At[m][k], acc[ai][bj][m][n], 0, 0, 0); __builtin_amdgcn_s_setprio(0); } while (0)
; #define PG8_WAIT_V(n) asm volatile("s_waitcnt vmcnt(" #n ")" ::: "memory")
; #define PG8_WAIT_L(n) asm volatile("s_waitcnt lgkmcnt(" #n ")" ::: "memory")
; #define PG8_BAR __builtin_amdgcn_s_barrier()
; #define PG8_SCHED __builtin_amdgcn_sched_barrier(0)
; template <class Epi, class Sched, bool ALIGN_EPI = false, bool SP2 = false>
; __device__ __forceinline__ void gemm_phase(PG8_LAS unsigned char* lds, const Gemm g, const Sched& S, const Epi& E, const int wid) {
;     ...
;             PG8_WAIT_V(8); PG8_WAIT_L(0); PG8_BAR; PG8_MMA(0, 0, At, B0); PG8_MMA(0, 1, At, B1); PG8_BAR; PG8_SCHED;
;             PG8_LDA(At, 0, 1); PG8_STAGE(PG8_SB(0, 0), b2, voffB); PG8_STAGE(PG8_SB(0, 1), b2 + hsB, voffB); PG8_STAGE(PG8_SA(0, 0), a2, voffA);
;             PG8_WAIT_V(8); PG8_WAIT_L(0); PG8_BAR; PG8_MMA(1, 0, At, B0); PG8_MMA(1, 1, At, B1); PG8_BAR; PG8_SCHED;
	s_waitcnt lgkmcnt(0)
	v_mfma_f32_16x16x32_bf16 v[126:129], v[130:133], v[186:189], v[126:129]
	v_mfma_f32_16x16x32_bf16 v[122:125], v[138:141], v[186:189], v[122:125]
	v_mfma_f32_16x16x32_bf16 v[110:113], v[130:133], v[194:197], v[110:113]
	v_mfma_f32_16x16x32_bf16 v[106:109], v[138:141], v[194:197], v[106:109]
	v_mfma_f32_16x16x32_bf16 v[94:97], v[130:133], v[202:205], v[94:97]
	v_mfma_f32_16x16x32_bf16 v[90:93], v[138:141], v[202:205], v[90:93]
	v_mfma_f32_16x16x32_bf16 v[78:81], v[130:133], v[210:213], v[78:81]
	v_mfma_f32_16x16x32_bf16 v[74:77], v[138:141], v[210:213], v[74:77]
	v_mfma_f32_16x16x32_bf16 v[126:129], v[134:137], v[190:193], v[126:129]
	v_mfma_f32_16x16x32_bf16 v[122:125], v[142:145], v[190:193], v[122:125]
	v_mfma_f32_16x16x32_bf16 v[110:113], v[134:137], v[198:201], v[110:113]
	v_mfma_f32_16x16x32_bf16 v[106:109], v[142:145], v[198:201], v[106:109]
	v_mfma_f32_16x16x32_bf16 v[94:97], v[134:137], v[206:209], v[94:97]
	v_mfma_f32_16x16x32_bf16 v[90:93], v[142:145], v[206:209], v[90:93]
	v_mfma_f32_16x16x32_bf16 v[78:81], v[134:137], v[214:217], v[78:81]
	v_mfma_f32_16x16x32_bf16 v[74:77], v[142:145], v[214:217], v[74:77]
	v_mfma_f32_16x16x32_bf16 v[118:121], v[146:149], v[186:189], v[118:121]
	v_mfma_f32_16x16x32_bf16 v[114:117], v[168:171], v[186:189], v[114:117]
	v_mfma_f32_16x16x32_bf16 v[102:105], v[146:149], v[194:197], v[102:105]
	v_mfma_f32_16x16x32_bf16 v[98:101], v[168:171], v[194:197], v[98:101]
	v_mfma_f32_16x16x32_bf16 v[86:89], v[146:149], v[202:205], v[86:89]
	v_mfma_f32_16x16x32_bf16 v[82:85], v[168:171], v[202:205], v[82:85]
	v_mfma_f32_16x16x32_bf16 v[70:73], v[146:149], v[210:213], v[70:73]
	v_mfma_f32_16x16x32_bf16 v[66:69], v[168:171], v[210:213], v[66:69]
	v_mfma_f32_16x16x32_bf16 v[118:121], v[164:167], v[190:193], v[118:121]
	v_mfma_f32_16x16x32_bf16 v[114:117], v[182:185], v[190:193], v[114:117]
	v_mfma_f32_16x16x32_bf16 v[102:105], v[164:167], v[198:201], v[102:105]
	v_mfma_f32_16x16x32_bf16 v[98:101], v[182:185], v[198:201], v[98:101]
	v_mfma_f32_16x16x32_bf16 v[86:89], v[164:167], v[206:209], v[86:89]
	v_mfma_f32_16x16x32_bf16 v[82:85], v[182:185], v[206:209], v[82:85]
	v_mfma_f32_16x16x32_bf16 v[70:73], v[164:167], v[214:217], v[70:73]
	v_mfma_f32_16x16x32_bf16 v[66:69], v[182:185], v[214:217], v[66:69]
	s_barrier
	s_add_i32 s24, s89, s28
	v_lshl_add_u64 v[172:173], s[72:73], 0, v[150:151]
	s_mov_b32 m0, s24
	ds_read_b128 v[186:189], v177 offset:16384
	ds_read_b128 v[190:193], v177 offset:17408
	ds_read_b128 v[194:197], v177 offset:18432
	ds_read_b128 v[198:201], v177 offset:19456
	ds_read_b128 v[202:205], v177 offset:20480
	ds_read_b128 v[206:209], v177 offset:21504
	ds_read_b128 v[210:213], v177 offset:22528
	ds_read_b128 v[214:217], v177 offset:23552
	global_load_lds_dwordx4 v[172:173], off
	s_add_i32 m0, s24, 0x2000
	s_add_u32 s24, s72, 0x40000
	v_lshl_add_u64 v[218:219], s[72:73], 0, v[152:153]
	s_addc_u32 s25, s73, 0
	s_add_i32 vcc_lo, s90, s28
	global_load_lds_dwordx4 v[218:219], off
	v_lshl_add_u64 v[220:221], s[24:25], 0, v[150:151]
	s_mov_b32 m0, vcc_lo
	v_lshl_add_u64 v[222:223], s[74:75], 0, v[152:153]
	global_load_lds_dwordx4 v[220:221], off
	v_lshl_add_u64 v[220:221], s[24:25], 0, v[152:153]
	s_add_i32 m0, vcc_lo, 0x2000
	s_nop 0
	global_load_lds_dwordx4 v[220:221], off
	v_lshl_add_u64 v[220:221], s[74:75], 0, v[150:151]
	s_mov_b32 m0, s71
	s_nop 0
	global_load_lds_dwordx4 v[220:221], off
	s_mov_b32 m0, s78
	s_nop 0
	global_load_lds_dwordx4 v[222:223], off
	s_waitcnt vmcnt(8)
	s_waitcnt lgkmcnt(0)
	s_barrier
	s_waitcnt lgkmcnt(0)
	v_mfma_f32_16x16x32_bf16 v[62:65], v[130:133], v[186:189], v[62:65]
	v_mfma_f32_16x16x32_bf16 v[58:61], v[138:141], v[186:189], v[58:61]
	v_mfma_f32_16x16x32_bf16 v[46:49], v[130:133], v[194:197], v[46:49]
	v_mfma_f32_16x16x32_bf16 v[42:45], v[138:141], v[194:197], v[42:45]
	v_mfma_f32_16x16x32_bf16 v[30:33], v[130:133], v[202:205], v[30:33]
	v_mfma_f32_16x16x32_bf16 v[26:29], v[138:141], v[202:205], v[26:29]
	v_mfma_f32_16x16x32_bf16 v[14:17], v[130:133], v[210:213], v[14:17]
	v_mfma_f32_16x16x32_bf16 v[10:13], v[138:141], v[210:213], v[10:13]
	v_mfma_f32_16x16x32_bf16 v[62:65], v[134:137], v[190:193], v[62:65]
	v_mfma_f32_16x16x32_bf16 v[58:61], v[142:145], v[190:193], v[58:61]
	v_mfma_f32_16x16x32_bf16 v[46:49], v[134:137], v[198:201], v[46:49]
	v_mfma_f32_16x16x32_bf16 v[42:45], v[142:145], v[198:201], v[42:45]
	v_mfma_f32_16x16x32_bf16 v[30:33], v[134:137], v[206:209], v[30:33]
	v_mfma_f32_16x16x32_bf16 v[26:29], v[142:145], v[206:209], v[26:29]
	v_mfma_f32_16x16x32_bf16 v[14:17], v[134:137], v[214:217], v[14:17]
	v_mfma_f32_16x16x32_bf16 v[10:13], v[142:145], v[214:217], v[10:13]
	v_mfma_f32_16x16x32_bf16 v[54:57], v[146:149], v[186:189], v[54:57]
	v_mfma_f32_16x16x32_bf16 v[50:53], v[168:171], v[186:189], v[50:53]
	v_mfma_f32_16x16x32_bf16 v[38:41], v[146:149], v[194:197], v[38:41]
	v_mfma_f32_16x16x32_bf16 v[34:37], v[168:171], v[194:197], v[34:37]
	v_mfma_f32_16x16x32_bf16 v[22:25], v[146:149], v[202:205], v[22:25]
	v_mfma_f32_16x16x32_bf16 v[18:21], v[168:171], v[202:205], v[18:21]
	v_mfma_f32_16x16x32_bf16 v[6:9], v[146:149], v[210:213], v[6:9]
	v_mfma_f32_16x16x32_bf16 v[2:5], v[168:171], v[210:213], v[2:5]
	v_mfma_f32_16x16x32_bf16 v[54:57], v[164:167], v[190:193], v[54:57]
	v_mfma_f32_16x16x32_bf16 v[50:53], v[182:185], v[190:193], v[50:53]
	v_mfma_f32_16x16x32_bf16 v[38:41], v[164:167], v[198:201], v[38:41]
	v_mfma_f32_16x16x32_bf16 v[34:37], v[182:185], v[198:201], v[34:37]
	v_mfma_f32_16x16x32_bf16 v[22:25], v[164:167], v[206:209], v[22:25]
	v_mfma_f32_16x16x32_bf16 v[18:21], v[182:185], v[206:209], v[18:21]
	v_mfma_f32_16x16x32_bf16 v[6:9], v[164:167], v[214:217], v[6:9]
	v_mfma_f32_16x16x32_bf16 v[2:5], v[182:185], v[214:217], v[2:5]
	s_barrier
; #define PG8_STAGE(bufoff, gbase, voff) do { _Pragma("unroll") for (int _i = 0; _i < 2; ++_i) \
;         __builtin_amdgcn_global_load_lds((const unsigned*)((const char*)(gbase) + (voff)[_i]), (PG8_LAS unsigned*)(lds + (bufoff) + ldsw + _i * 8192), 16, 0, 0); } while (0)
; #define PG8_LDA(dst, b, h) do { _Pragma("unroll") for (int m = 0; m < 4; ++m) _Pragma("unroll") for (int k = 0; k < 2; ++k) dst[m][k] = *(const PG8_LAS bf16x8*)(lds + PG8_SA(b, h) + aoff + m * 2048 + k * 1024); } while (0)
; #define PG8_LDB(dst, b, h) do { _Pragma("unroll") for (int n = 0; n < 2; ++n) _Pragma("unroll") for (int k = 0; k < 2; ++k) dst[n][k] = *(const PG8_LAS bf16x8*)(lds + PG8_SB(b, h) + boff + n * 2048 + k * 1024); } while (0)
; #define PG8_MMA(ai, bj, At, Bt) do { __builtin_amdgcn_s_setprio(1); _Pragma("unroll") for (int m = 0; m < 4; ++m) _Pragma("unroll") for (int n = 0; n < 2; ++n) _Pragma("unroll") for (int k = 0; k < 2; ++k) \
;         acc[ai][bj][m][n] = __builtin_amdgcn_mfma_f32_16x16x32_bf16(Bt[n][k], At[m][k], acc[ai][bj][m][n], 0, 0, 0); __builtin_amdgcn_s_setprio(0); } while (0)
; #define PG8_WAIT_V(n) asm volatile("s_waitcnt vmcnt(" #n ")" ::: "memory")
; #define PG8_WAIT_L(n) asm volatile("s_waitcnt lgkmcnt(" #n ")" ::: "memory")
; #define PG8_BAR __builtin_amdgcn_s_barrier()
; #define PG8_SCHED __builtin_amdgcn_sched_barrier(0)
; template <class Epi, class Sched, bool ALIGN_EPI = false, bool SP2 = false>
; __device__ __forceinline__ void gemm_phase(PG8_LAS unsigned char* lds, const Gemm g, const Sched& S, const Epi& E, const int wid) {
;     ...
;             PG8_LDB(B0, 1, 0); PG8_LDB(B1, 1, 1); PG8_SCHED; PG8_LDA(At, 1, 0); PG8_STAGE(PG8_SA(0, 1), a2 + hsA, voffA);
;             PG8_WAIT_V(8); PG8_WAIT_L(0); PG8_BAR; PG8_MMA(0, 0, At, B0); PG8_MMA(0, 1, At, B1); PG8_BAR; PG8_SCHED;
	s_add_i32 vcc_lo, 0, 0x18000
	s_add_i32 vcc_hi, 0, 0x1c000
	v_add_u32_e32 v142, vcc_lo, v174
	v_add_u32_e32 v154, vcc_hi, v174
	ds_read_b128 v[130:133], v142
	ds_read_b128 v[134:137], v142 offset:1024
	ds_read_b128 v[138:141], v142 offset:2048
	ds_read_b128 v[142:145], v142 offset:3072
	ds_read_b128 v[146:149], v154
	ds_read_b128 v[164:167], v154 offset:1024
	ds_read_b128 v[168:171], v154 offset:2048
	ds_read_b128 v[182:185], v154 offset:3072
	s_add_u32 s24, s74, 0x40000
	s_addc_u32 s25, s75, 0
	s_mov_b32 m0, s79
	v_lshl_add_u64 v[224:225], s[24:25], 0, v[150:151]
	ds_read_b128 v[186:189], v177 offset:32768
	ds_read_b128 v[190:193], v177 offset:33792
	ds_read_b128 v[194:197], v177 offset:34816
	ds_read_b128 v[198:201], v177 offset:35840
	ds_read_b128 v[202:205], v177 offset:36864
	ds_read_b128 v[206:209], v177 offset:37888
	ds_read_b128 v[210:213], v177 offset:38912
	ds_read_b128 v[214:217], v177 offset:39936
	global_load_lds_dwordx4 v[224:225], off
	v_lshl_add_u64 v[224:225], s[24:25], 0, v[152:153]
	s_mov_b32 m0, s80
	s_nop 0
	global_load_lds_dwordx4 v[224:225], off
	s_waitcnt vmcnt(8)
	s_waitcnt lgkmcnt(0)
	s_barrier
	s_waitcnt lgkmcnt(0)
	v_mfma_f32_16x16x32_bf16 v[126:129], v[130:133], v[186:189], v[126:129]
	v_mfma_f32_16x16x32_bf16 v[122:125], v[138:141], v[186:189], v[122:125]
	v_mfma_f32_16x16x32_bf16 v[110:113], v[130:133], v[194:197], v[110:113]
	v_mfma_f32_16x16x32_bf16 v[106:109], v[138:141], v[194:197], v[106:109]
	v_mfma_f32_16x16x32_bf16 v[94:97], v[130:133], v[202:205], v[94:97]
	v_mfma_f32_16x16x32_bf16 v[90:93], v[138:141], v[202:205], v[90:93]
	v_mfma_f32_16x16x32_bf16 v[78:81], v[130:133], v[210:213], v[78:81]
	v_mfma_f32_16x16x32_bf16 v[74:77], v[138:141], v[210:213], v[74:77]
	v_mfma_f32_16x16x32_bf16 v[126:129], v[134:137], v[190:193], v[126:129]
	v_mfma_f32_16x16x32_bf16 v[122:125], v[142:145], v[190:193], v[122:125]
	v_mfma_f32_16x16x32_bf16 v[110:113], v[134:137], v[198:201], v[110:113]
	v_mfma_f32_16x16x32_bf16 v[106:109], v[142:145], v[198:201], v[106:109]
	v_mfma_f32_16x16x32_bf16 v[94:97], v[134:137], v[206:209], v[94:97]
	v_mfma_f32_16x16x32_bf16 v[90:93], v[142:145], v[206:209], v[90:93]
	v_mfma_f32_16x16x32_bf16 v[78:81], v[134:137], v[214:217], v[78:81]
	v_mfma_f32_16x16x32_bf16 v[74:77], v[142:145], v[214:217], v[74:77]
	v_mfma_f32_16x16x32_bf16 v[118:121], v[146:149], v[186:189], v[118:121]
	v_mfma_f32_16x16x32_bf16 v[114:117], v[168:171], v[186:189], v[114:117]
	v_mfma_f32_16x16x32_bf16 v[102:105], v[146:149], v[194:197], v[102:105]
	v_mfma_f32_16x16x32_bf16 v[98:101], v[168:171], v[194:197], v[98:101]
	v_mfma_f32_16x16x32_bf16 v[86:89], v[146:149], v[202:205], v[86:89]
	v_mfma_f32_16x16x32_bf16 v[82:85], v[168:171], v[202:205], v[82:85]
	v_mfma_f32_16x16x32_bf16 v[70:73], v[146:149], v[210:213], v[70:73]
	v_mfma_f32_16x16x32_bf16 v[66:69], v[168:171], v[210:213], v[66:69]
	v_mfma_f32_16x16x32_bf16 v[118:121], v[164:167], v[190:193], v[118:121]
	v_mfma_f32_16x16x32_bf16 v[114:117], v[182:185], v[190:193], v[114:117]
	v_mfma_f32_16x16x32_bf16 v[102:105], v[164:167], v[198:201], v[102:105]
	v_mfma_f32_16x16x32_bf16 v[98:101], v[182:185], v[198:201], v[98:101]
	v_mfma_f32_16x16x32_bf16 v[86:89], v[164:167], v[206:209], v[86:89]
	v_mfma_f32_16x16x32_bf16 v[82:85], v[182:185], v[206:209], v[82:85]
	v_mfma_f32_16x16x32_bf16 v[70:73], v[164:167], v[214:217], v[70:73]
	v_mfma_f32_16x16x32_bf16 v[66:69], v[182:185], v[214:217], v[66:69]
	s_barrier
; #define PG8_STAGE(bufoff, gbase, voff) do { _Pragma("unroll") for (int _i = 0; _i < 2; ++_i) \
;         __builtin_amdgcn_global_load_lds((const unsigned*)((const char*)(gbase) + (voff)[_i]), (PG8_LAS unsigned*)(lds + (bufoff) + ldsw + _i * 8192), 16, 0, 0); } while (0)
; #define PG8_LDA(dst, b, h) do { _Pragma("unroll") for (int m = 0; m < 4; ++m) _Pragma("unroll") for (int k = 0; k < 2; ++k) dst[m][k] = *(const PG8_LAS bf16x8*)(lds + PG8_SA(b, h) + aoff + m * 2048 + k * 1024); } while (0)
; #define PG8_MMA(ai, bj, At, Bt) do { __builtin_amdgcn_s_setprio(1); _Pragma("unroll") for (int m = 0; m < 4; ++m) _Pragma("unroll") for (int n = 0; n < 2; ++n) _Pragma("unroll") for (int k = 0; k < 2; ++k) \
;         acc[ai][bj][m][n] = __builtin_amdgcn_mfma_f32_16x16x32_bf16(Bt[n][k], At[m][k], acc[ai][bj][m][n], 0, 0, 0); __builtin_amdgcn_s_setprio(0); } while (0)
; #define PG8_WAIT_V(n) asm volatile("s_waitcnt vmcnt(" #n ")" ::: "memory")
; #define PG8_WAIT_L(n) asm volatile("s_waitcnt lgkmcnt(" #n ")" ::: "memory")
; #define PG8_BAR __builtin_amdgcn_s_barrier()
; #define PG8_SCHED __builtin_amdgcn_sched_barrier(0)
; template <class Epi, class Sched, bool ALIGN_EPI = false, bool SP2 = false>
; __device__ __forceinline__ void gemm_phase(PG8_LAS unsigned char* lds, const Gemm g, const Sched& S, const Epi& E, const int wid) {
;     ...
;             PG8_LDA(At, 1, 1); PG8_STAGE(PG8_SB(1, 0), b3, voffB); PG8_STAGE(PG8_SB(1, 1), b3 + hsB, voffB); PG8_STAGE(PG8_SA(1, 0), a3, voffA);
;             PG8_WAIT_V(8); PG8_WAIT_L(0); PG8_BAR; PG8_MMA(1, 0, At, B0); PG8_MMA(1, 1, At, B1); PG8_BAR; PG8_SCHED;
;     ...
;         if constexpr (ALIGN_EPI) { if (wr == 0) PG8_BAR; }
	s_add_i32 s24, vcc_lo, s28
	v_lshl_add_u64 v[172:173], v[172:173], 0, s[44:45]
	s_mov_b32 m0, s24
	ds_read_b128 v[186:189], v177 offset:49152
	ds_read_b128 v[190:193], v177 offset:50176
	ds_read_b128 v[194:197], v177 offset:51200
	ds_read_b128 v[198:201], v177 offset:52224
	ds_read_b128 v[202:205], v177 offset:53248
	ds_read_b128 v[206:209], v177 offset:54272
	ds_read_b128 v[210:213], v177 offset:55296
	ds_read_b128 v[214:217], v177 offset:56320
	global_load_lds_dwordx4 v[172:173], off
	s_add_i32 m0, s24, 0x2000
	s_add_u32 s24, s72, 0x40080
	v_lshl_add_u64 v[172:173], v[218:219], 0, s[44:45]
	s_addc_u32 s25, s73, 0
	s_add_i32 s72, vcc_hi, s28
	global_load_lds_dwordx4 v[172:173], off
	v_lshl_add_u64 v[172:173], s[24:25], 0, v[150:151]
	s_mov_b32 m0, s72
	s_nop 0
	global_load_lds_dwordx4 v[172:173], off
	v_lshl_add_u64 v[172:173], s[24:25], 0, v[152:153]
	s_add_i32 m0, s72, 0x2000
	s_nop 0
	global_load_lds_dwordx4 v[172:173], off
	v_lshl_add_u64 v[172:173], v[220:221], 0, s[44:45]
	s_mov_b32 m0, s83
	s_nop 0
	global_load_lds_dwordx4 v[172:173], off
	v_lshl_add_u64 v[172:173], v[222:223], 0, s[44:45]
	s_mov_b32 m0, s84
	s_nop 0
	global_load_lds_dwordx4 v[172:173], off
	s_waitcnt vmcnt(8)
	s_waitcnt lgkmcnt(0)
	s_barrier
	s_waitcnt lgkmcnt(0)
	v_mfma_f32_16x16x32_bf16 v[62:65], v[130:133], v[186:189], v[62:65]
	v_mfma_f32_16x16x32_bf16 v[58:61], v[138:141], v[186:189], v[58:61]
	v_mfma_f32_16x16x32_bf16 v[46:49], v[130:133], v[194:197], v[46:49]
	v_mfma_f32_16x16x32_bf16 v[42:45], v[138:141], v[194:197], v[42:45]
	v_mfma_f32_16x16x32_bf16 v[30:33], v[130:133], v[202:205], v[30:33]
	v_mfma_f32_16x16x32_bf16 v[26:29], v[138:141], v[202:205], v[26:29]
	v_mfma_f32_16x16x32_bf16 v[14:17], v[130:133], v[210:213], v[14:17]
	v_mfma_f32_16x16x32_bf16 v[10:13], v[138:141], v[210:213], v[10:13]
	v_mfma_f32_16x16x32_bf16 v[62:65], v[134:137], v[190:193], v[62:65]
	v_mfma_f32_16x16x32_bf16 v[58:61], v[142:145], v[190:193], v[58:61]
	v_mfma_f32_16x16x32_bf16 v[46:49], v[134:137], v[198:201], v[46:49]
	v_mfma_f32_16x16x32_bf16 v[42:45], v[142:145], v[198:201], v[42:45]
	v_mfma_f32_16x16x32_bf16 v[30:33], v[134:137], v[206:209], v[30:33]
	v_mfma_f32_16x16x32_bf16 v[26:29], v[142:145], v[206:209], v[26:29]
	v_mfma_f32_16x16x32_bf16 v[14:17], v[134:137], v[214:217], v[14:17]
	v_mfma_f32_16x16x32_bf16 v[10:13], v[142:145], v[214:217], v[10:13]
	v_mfma_f32_16x16x32_bf16 v[54:57], v[146:149], v[186:189], v[54:57]
	v_mfma_f32_16x16x32_bf16 v[50:53], v[168:171], v[186:189], v[50:53]
	v_mfma_f32_16x16x32_bf16 v[38:41], v[146:149], v[194:197], v[38:41]
	v_mfma_f32_16x16x32_bf16 v[34:37], v[168:171], v[194:197], v[34:37]
	v_mfma_f32_16x16x32_bf16 v[22:25], v[146:149], v[202:205], v[22:25]
	v_mfma_f32_16x16x32_bf16 v[18:21], v[168:171], v[202:205], v[18:21]
	v_mfma_f32_16x16x32_bf16 v[6:9], v[146:149], v[210:213], v[6:9]
	v_mfma_f32_16x16x32_bf16 v[2:5], v[168:171], v[210:213], v[2:5]
	v_mfma_f32_16x16x32_bf16 v[54:57], v[164:167], v[190:193], v[54:57]
	v_mfma_f32_16x16x32_bf16 v[50:53], v[182:185], v[190:193], v[50:53]
	v_mfma_f32_16x16x32_bf16 v[38:41], v[164:167], v[198:201], v[38:41]
	v_mfma_f32_16x16x32_bf16 v[34:37], v[182:185], v[198:201], v[34:37]
	v_mfma_f32_16x16x32_bf16 v[22:25], v[164:167], v[206:209], v[22:25]
	v_mfma_f32_16x16x32_bf16 v[18:21], v[182:185], v[206:209], v[18:21]
	v_mfma_f32_16x16x32_bf16 v[6:9], v[164:167], v[214:217], v[6:9]
	v_mfma_f32_16x16x32_bf16 v[2:5], v[182:185], v[214:217], v[2:5]
	s_barrier
	s_add_i32 s65, s65, 2
	s_add_u32 s8, s8, 0x100
	s_addc_u32 s9, s9, 0
	s_add_u32 s34, s34, 0x100
	s_addc_u32 s63, s63, 0
	s_cmp_gt_u32 s65, 13
	s_cbranch_scc0 .LBB0_236
	s_setprio 0
	s_and_b64 vcc, exec, s[46:47]
	s_cbranch_vccz .LBB0_239
	s_barrier

;     __device__ __forceinline__ const char* a_ptr(const Gemm& g, const Unit& u, size_t tsA) const { return (const char*)g.A + (size_t)u.pm * tsA + (size_t)u.pn * g.a_pn_bytes + (u.ks > 0 ? (size_t)u.ks * g.ks_bytes : 0); }
;     __device__ __forceinline__ const char* b_ptr(const Gemm& g, const Unit& u, size_t tsB) const { return (const char*)g.Bt + (size_t)u.pn * tsB + (u.ks > 0 ? (size_t)u.ks * g.ks_bytes : 0); }
;     __device__ __forceinline__ const char* a_ptr(const Gemm& g, const Unit& u, size_t tsA) const { return (const char*)g.A + (size_t)u.pm * tsA + (size_t)u.pn * g.a_pn_bytes + (u.ks > 0 ? (size_t)u.ks * g.ks_bytes : 0); }
;     __device__ __forceinline__ const char* b_ptr(const Gemm& g, const Unit& u, size_t tsB) const { return (const char*)g.Bt + (size_t)u.pn * tsB + (u.ks > 0 ? (size_t)u.ks * g.ks_bytes : 0); }
; #define PG8_LDA(dst, b, h) do { _Pragma("unroll") for (int m = 0; m < 4; ++m) _Pragma("unroll") for (int k = 0; k < 2; ++k) dst[m][k] = *(const PG8_LAS bf16x8*)(lds + PG8_SA(b, h) + aoff + m * 2048 + k * 1024); } while (0)
; template <class Epi, class Sched, bool ALIGN_EPI = false, bool SP2 = false>
; __device__ __forceinline__ void gemm_phase(PG8_LAS unsigned char* lds, const Gemm g, const Sched& S, const Epi& E, const int wid) {
;     ...
;         const bool has_next = S.next(ui + 1, nxt);
;         const char* nA = has_next ? S.a_ptr(g, nxt, tsA) : cA; const char* nB = has_next ? S.b_ptr(g, nxt, tsB) : cB;
;         const int nt = cur.ks >= 0 ? g.nt_split : ntfull;
; #pragma unroll 1
;         for (int t = 0; t < nt; t += 2) {
;             const bool last = (t == nt - 2);
;             const char* a1 = cA + (size_t)(t + 1) * kstep;
;             const char* a2 = last ? nA : cA + (size_t)(t + 2) * kstep; const char* b2 = last ? nB : cB + (size_t)(t + 2) * kstep;
;             const char* a3 = a2 + kstep; const char* b3 = b2 + kstep;
;             if (last && has_next) S.a_ready(nxt);
;             if constexpr (SP2) {
;             PG8_LDB(B0, 0, 0); PG8_LDB(B1, 0, 1); PG8_SCHED; PG8_LDA(At, 0, 0); PG8_STAGE(PG8_SA(1, 1), a1 + hsA, voffA);
;     ...
; #pragma unroll
;         for (int a = 0; a < 2; ++a)
; #pragma unroll
;             for (int b = 0; b < 2; ++b)
; #pragma unroll
;                 for (int m = 0; m < 4; ++m)
; #pragma unroll
;                     for (int n = 0; n < 2; ++n) acc[a][b][m][n] = (f32x4){0.f, 0.f, 0.f, 0.f};
.LBB0_1280:
	s_lshl_b64 s[24:25], s[38:39], 9
	s_cmp_gt_i32 s38, 0
	s_cselect_b32 s75, s25, 0
	s_cselect_b32 s74, s24, 0
	s_ashr_i32 s69, s68, 31
	s_lshl_b64 s[24:25], s[68:69], 19
	s_add_u32 s15, s31, s24
	s_addc_u32 s24, s35, s25
	s_add_u32 s72, s15, s74
	s_addc_u32 s73, s24, s75
	s_and_b64 s[24:25], s[66:67], exec
	s_cselect_b32 s15, s73, s13
	s_cselect_b32 s47, s72, s12
	s_ashr_i32 s71, s70, 31
	s_lshl_b64 s[24:25], s[70:71], 19
	s_add_u32 s24, s87, s24
	s_addc_u32 s25, s88, s25
	s_add_u32 s74, s24, s74
	s_addc_u32 s75, s25, s75
	s_and_b64 s[24:25], s[66:67], exec
	s_cselect_b32 s69, s75, s79
	s_cselect_b32 s71, s74, s78
	s_cmp_lt_i32 s46, 0
	s_cselect_b32 s77, 16, 4
	s_add_i32 s82, s77, -2
	s_add_u32 s12, s12, 0x40080
	s_addc_u32 s13, s13, 0
	s_add_u32 s83, s78, 0x100
	v_mov_b32_e32 v2, 0
	s_mov_b32 s80, 0
	s_addc_u32 vcc_lo, s79, 0
	v_mov_b32_e32 v3, v2
	v_mov_b32_e32 v4, v2
	v_mov_b32_e32 v5, v2
	v_mov_b32_e32 v6, v2
	v_mov_b32_e32 v7, v2
	v_mov_b32_e32 v8, v2
	v_mov_b32_e32 v9, v2
	v_mov_b32_e32 v10, v2
	v_mov_b32_e32 v11, v2
	v_mov_b32_e32 v12, v2
	v_mov_b32_e32 v13, v2
	v_mov_b32_e32 v14, v2
	v_mov_b32_e32 v15, v2
	v_mov_b32_e32 v16, v2
	v_mov_b32_e32 v17, v2
	v_mov_b32_e32 v22, v2
	v_mov_b32_e32 v23, v2
	v_mov_b32_e32 v24, v2
	v_mov_b32_e32 v25, v2
	v_mov_b32_e32 v30, v2
	v_mov_b32_e32 v31, v2
	v_mov_b32_e32 v32, v2
	v_mov_b32_e32 v33, v2
	v_mov_b32_e32 v38, v2
	v_mov_b32_e32 v39, v2
	v_mov_b32_e32 v40, v2
	v_mov_b32_e32 v41, v2
	v_mov_b32_e32 v46, v2
	v_mov_b32_e32 v47, v2
	v_mov_b32_e32 v48, v2
	v_mov_b32_e32 v49, v2
	v_mov_b32_e32 v18, v2
	v_mov_b32_e32 v19, v2
	v_mov_b32_e32 v20, v2
	v_mov_b32_e32 v21, v2
	v_mov_b32_e32 v26, v2
	v_mov_b32_e32 v27, v2
	v_mov_b32_e32 v28, v2
	v_mov_b32_e32 v29, v2
	v_mov_b32_e32 v34, v2
	v_mov_b32_e32 v35, v2
	v_mov_b32_e32 v36, v2
	v_mov_b32_e32 v37, v2
	v_mov_b32_e32 v42, v2
	v_mov_b32_e32 v43, v2
	v_mov_b32_e32 v44, v2
	v_mov_b32_e32 v45, v2
	v_mov_b32_e32 v50, v2
	v_mov_b32_e32 v51, v2
	v_mov_b32_e32 v52, v2
	v_mov_b32_e32 v53, v2
	v_mov_b32_e32 v54, v2
	v_mov_b32_e32 v55, v2
	v_mov_b32_e32 v56, v2
	v_mov_b32_e32 v57, v2
	v_mov_b32_e32 v58, v2
	v_mov_b32_e32 v59, v2
	v_mov_b32_e32 v60, v2
	v_mov_b32_e32 v61, v2
	v_mov_b32_e32 v62, v2
	v_mov_b32_e32 v63, v2
	v_mov_b32_e32 v64, v2
	v_mov_b32_e32 v65, v2
	v_mov_b32_e32 v66, v2
	v_mov_b32_e32 v67, v2
	v_mov_b32_e32 v68, v2
	v_mov_b32_e32 v69, v2
	v_mov_b32_e32 v70, v2
	v_mov_b32_e32 v71, v2
	v_mov_b32_e32 v72, v2
	v_mov_b32_e32 v73, v2
	v_mov_b32_e32 v74, v2
	v_mov_b32_e32 v75, v2
	v_mov_b32_e32 v76, v2
	v_mov_b32_e32 v77, v2
	v_mov_b32_e32 v78, v2
	v_mov_b32_e32 v79, v2
	v_mov_b32_e32 v80, v2
	v_mov_b32_e32 v81, v2
	v_mov_b32_e32 v86, v2
	v_mov_b32_e32 v87, v2
	v_mov_b32_e32 v88, v2
	v_mov_b32_e32 v89, v2
	v_mov_b32_e32 v94, v2
	v_mov_b32_e32 v95, v2
	v_mov_b32_e32 v96, v2
	v_mov_b32_e32 v97, v2
	v_mov_b32_e32 v102, v2
	v_mov_b32_e32 v103, v2
	v_mov_b32_e32 v104, v2
	v_mov_b32_e32 v105, v2
	v_mov_b32_e32 v110, v2
	v_mov_b32_e32 v111, v2
	v_mov_b32_e32 v112, v2
	v_mov_b32_e32 v113, v2
	v_mov_b32_e32 v82, v2
	v_mov_b32_e32 v83, v2
	v_mov_b32_e32 v84, v2
	v_mov_b32_e32 v85, v2
	v_mov_b32_e32 v90, v2
	v_mov_b32_e32 v91, v2
	v_mov_b32_e32 v92, v2
	v_mov_b32_e32 v93, v2
	v_mov_b32_e32 v98, v2
	v_mov_b32_e32 v99, v2
	v_mov_b32_e32 v100, v2
	v_mov_b32_e32 v101, v2
	v_mov_b32_e32 v106, v2
	v_mov_b32_e32 v107, v2
	v_mov_b32_e32 v108, v2
	v_mov_b32_e32 v109, v2
	v_mov_b32_e32 v114, v2
	v_mov_b32_e32 v115, v2
	v_mov_b32_e32 v116, v2
	v_mov_b32_e32 v117, v2
	v_mov_b32_e32 v118, v2
	v_mov_b32_e32 v119, v2
	v_mov_b32_e32 v120, v2
	v_mov_b32_e32 v121, v2
	s_waitcnt vmcnt(0)
	v_mov_b32_e32 v122, v2
	v_mov_b32_e32 v123, v2
	v_mov_b32_e32 v124, v2
	v_mov_b32_e32 v125, v2
	v_mov_b32_e32 v126, v2
	v_mov_b32_e32 v127, v2
	v_mov_b32_e32 v128, v2
	v_mov_b32_e32 v129, v2
	s_cmp_lg_u64 s[6:7], 0
	s_cbranch_scc1 .Lsprio1
	s_setprio 1
.Lsprio1:
.LBB0_1281:
	ds_read_b128 v[130:133], v230
	ds_read_b128 v[134:137], v230 offset:1024
	ds_read_b128 v[138:141], v230 offset:2048
	ds_read_b128 v[142:145], v230 offset:3072
	ds_read_b128 v[146:149], v231
	ds_read_b128 v[150:153], v231 offset:1024
	ds_read_b128 v[154:157], v231 offset:2048
	ds_read_b128 v[158:161], v231 offset:3072
	s_add_i32 vcc_hi, s80, 2
	s_add_u32 s24, s12, 0xfffc0080
	s_addc_u32 s25, s13, -1
	s_cmp_eq_u32 s82, s80
	s_cselect_b32 s80, s47, s24
	s_cselect_b32 s81, s15, s25
	s_cselect_b32 s79, s69, vcc_lo
	s_cselect_b32 s78, s71, s83
	v_lshl_add_u64 v[206:207], s[12:13], 0, v[190:191]
	s_add_i32 m0, s85, 0xc000
	ds_read_b128 v[162:165], v232
	ds_read_b128 v[166:169], v232 offset:1024
	ds_read_b128 v[170:173], v232 offset:2048
	ds_read_b128 v[174:177], v232 offset:3072
	ds_read_b128 v[178:181], v232 offset:4096
	ds_read_b128 v[182:185], v232 offset:5120
	ds_read_b128 v[198:201], v232 offset:6144
	ds_read_b128 v[202:205], v232 offset:7168
	global_load_lds_dwordx4 v[206:207], off
	v_lshl_add_u64 v[206:207], s[12:13], 0, v[192:193]
	s_add_i32 m0, s85, 0xe000
	s_nop 0
	global_load_lds_dwordx4 v[206:207], off
	s_waitcnt vmcnt(8)
	s_waitcnt lgkmcnt(0)
	s_barrier
; #define PG8_STAGE(bufoff, gbase, voff) do { _Pragma("unroll") for (int _i = 0; _i < 2; ++_i) \
;         __builtin_amdgcn_global_load_lds((const unsigned*)((const char*)(gbase) + (voff)[_i]), (PG8_LAS unsigned*)(lds + (bufoff) + ldsw + _i * 8192), 16, 0, 0); } while (0)
; #define PG8_LDA(dst, b, h) do { _Pragma("unroll") for (int m = 0; m < 4; ++m) _Pragma("unroll") for (int k = 0; k < 2; ++k) dst[m][k] = *(const PG8_LAS bf16x8*)(lds + PG8_SA(b, h) + aoff + m * 2048 + k * 1024); } while (0)
; #define PG8_MMA(ai, bj, At, Bt) do { __builtin_amdgcn_s_setprio(1); _Pragma("unroll") for (int m = 0; m < 4; ++m) _Pragma("unroll") for (int n = 0; n < 2; ++n) _Pragma("unroll") for (int k = 0; k < 2; ++k) \
;         acc[ai][bj][m][n] = __builtin_amdgcn_mfma_f32_16x16x32_bf16(Bt[n][k], At[m][k], acc[ai][bj][m][n], 0, 0, 0); __builtin_amdgcn_s_setprio(0); } while (0)
; #define PG8_WAIT_V(n) asm volatile("s_waitcnt vmcnt(" #n ")" ::: "memory")
; #define PG8_WAIT_L(n) asm volatile("s_waitcnt lgkmcnt(" #n ")" ::: "memory")
; #define PG8_BAR __builtin_amdgcn_s_barrier()
; #define PG8_SCHED __builtin_amdgcn_sched_barrier(0)
; template <class Epi, class Sched, bool ALIGN_EPI = false, bool SP2 = false>
; __device__ __forceinline__ void gemm_phase(PG8_LAS unsigned char* lds, const Gemm g, const Sched& S, const Epi& E, const int wid) {
;     ...
;             PG8_WAIT_V(8); PG8_WAIT_L(0); PG8_BAR; PG8_MMA(0, 0, At, B0); PG8_MMA(0, 1, At, B1); PG8_BAR; PG8_SCHED;
;             PG8_LDA(At, 0, 1); PG8_STAGE(PG8_SB(0, 0), b2, voffB); PG8_STAGE(PG8_SB(0, 1), b2 + hsB, voffB); PG8_STAGE(PG8_SA(0, 0), a2, voffA);
;             PG8_WAIT_V(8); PG8_WAIT_L(0); PG8_BAR; PG8_MMA(1, 0, At, B0); PG8_MMA(1, 1, At, B1); PG8_BAR; PG8_SCHED;
	s_waitcnt lgkmcnt(0)
	v_mfma_f32_16x16x32_bf16 v[126:129], v[130:133], v[162:165], v[126:129]
	v_mfma_f32_16x16x32_bf16 v[122:125], v[138:141], v[162:165], v[122:125]
	v_mfma_f32_16x16x32_bf16 v[118:121], v[130:133], v[170:173], v[118:121]
	v_mfma_f32_16x16x32_bf16 v[114:117], v[138:141], v[170:173], v[114:117]
	v_mfma_f32_16x16x32_bf16 v[106:109], v[130:133], v[178:181], v[106:109]
	v_mfma_f32_16x16x32_bf16 v[98:101], v[138:141], v[178:181], v[98:101]
	v_mfma_f32_16x16x32_bf16 v[90:93], v[130:133], v[198:201], v[90:93]
	v_mfma_f32_16x16x32_bf16 v[82:85], v[138:141], v[198:201], v[82:85]
	v_mfma_f32_16x16x32_bf16 v[126:129], v[134:137], v[166:169], v[126:129]
	v_mfma_f32_16x16x32_bf16 v[122:125], v[142:145], v[166:169], v[122:125]
	v_mfma_f32_16x16x32_bf16 v[118:121], v[134:137], v[174:177], v[118:121]
	v_mfma_f32_16x16x32_bf16 v[114:117], v[142:145], v[174:177], v[114:117]
	v_mfma_f32_16x16x32_bf16 v[106:109], v[134:137], v[182:185], v[106:109]
	v_mfma_f32_16x16x32_bf16 v[98:101], v[142:145], v[182:185], v[98:101]
	v_mfma_f32_16x16x32_bf16 v[90:93], v[134:137], v[202:205], v[90:93]
	v_mfma_f32_16x16x32_bf16 v[82:85], v[142:145], v[202:205], v[82:85]
	v_mfma_f32_16x16x32_bf16 v[110:113], v[146:149], v[162:165], v[110:113]
	v_mfma_f32_16x16x32_bf16 v[102:105], v[154:157], v[162:165], v[102:105]
	v_mfma_f32_16x16x32_bf16 v[94:97], v[146:149], v[170:173], v[94:97]
	v_mfma_f32_16x16x32_bf16 v[86:89], v[154:157], v[170:173], v[86:89]
	v_mfma_f32_16x16x32_bf16 v[78:81], v[146:149], v[178:181], v[78:81]
	v_mfma_f32_16x16x32_bf16 v[74:77], v[154:157], v[178:181], v[74:77]
	v_mfma_f32_16x16x32_bf16 v[70:73], v[146:149], v[198:201], v[70:73]
	v_mfma_f32_16x16x32_bf16 v[66:69], v[154:157], v[198:201], v[66:69]
	v_mfma_f32_16x16x32_bf16 v[110:113], v[150:153], v[166:169], v[110:113]
	v_mfma_f32_16x16x32_bf16 v[102:105], v[158:161], v[166:169], v[102:105]
	v_mfma_f32_16x16x32_bf16 v[94:97], v[150:153], v[174:177], v[94:97]
	v_mfma_f32_16x16x32_bf16 v[86:89], v[158:161], v[174:177], v[86:89]
	v_mfma_f32_16x16x32_bf16 v[78:81], v[150:153], v[182:185], v[78:81]
	v_mfma_f32_16x16x32_bf16 v[74:77], v[158:161], v[182:185], v[74:77]
	v_mfma_f32_16x16x32_bf16 v[70:73], v[150:153], v[202:205], v[70:73]
	v_mfma_f32_16x16x32_bf16 v[66:69], v[158:161], v[202:205], v[66:69]
	s_barrier
	s_add_i32 s24, s36, s28
	v_lshl_add_u64 v[206:207], s[78:79], 0, v[186:187]
	s_mov_b32 m0, s24
	ds_read_b128 v[162:165], v232 offset:16384
	ds_read_b128 v[166:169], v232 offset:17408
	ds_read_b128 v[170:173], v232 offset:18432
	ds_read_b128 v[174:177], v232 offset:19456
	ds_read_b128 v[178:181], v232 offset:20480
	ds_read_b128 v[182:185], v232 offset:21504
	ds_read_b128 v[198:201], v232 offset:22528
	ds_read_b128 v[202:205], v232 offset:23552
	global_load_lds_dwordx4 v[206:207], off
	s_add_i32 m0, s24, 0x2000
	s_add_u32 s24, s78, 0x40000
	v_lshl_add_u64 v[208:209], s[78:79], 0, v[188:189]
	s_addc_u32 s25, s79, 0
	s_add_i32 s8, s34, s28
	global_load_lds_dwordx4 v[208:209], off
	v_lshl_add_u64 v[210:211], s[24:25], 0, v[186:187]
	s_mov_b32 m0, s8
	v_lshl_add_u64 v[212:213], s[80:81], 0, v[188:189]
	global_load_lds_dwordx4 v[210:211], off
	v_lshl_add_u64 v[210:211], s[24:25], 0, v[188:189]
	s_add_i32 m0, s8, 0x2000
	s_nop 0
	global_load_lds_dwordx4 v[210:211], off
	v_lshl_add_u64 v[210:211], s[80:81], 0, v[186:187]
	s_mov_b32 m0, s85
	s_nop 0
	global_load_lds_dwordx4 v[210:211], off
	s_mov_b32 m0, s89
	s_nop 0
	global_load_lds_dwordx4 v[212:213], off
	s_waitcnt vmcnt(8)
	s_waitcnt lgkmcnt(0)
	s_barrier
	s_waitcnt lgkmcnt(0)
	v_mfma_f32_16x16x32_bf16 v[62:65], v[130:133], v[162:165], v[62:65]
	v_mfma_f32_16x16x32_bf16 v[58:61], v[138:141], v[162:165], v[58:61]
	v_mfma_f32_16x16x32_bf16 v[54:57], v[130:133], v[170:173], v[54:57]
	v_mfma_f32_16x16x32_bf16 v[50:53], v[138:141], v[170:173], v[50:53]
	v_mfma_f32_16x16x32_bf16 v[42:45], v[130:133], v[178:181], v[42:45]
	v_mfma_f32_16x16x32_bf16 v[34:37], v[138:141], v[178:181], v[34:37]
	v_mfma_f32_16x16x32_bf16 v[26:29], v[130:133], v[198:201], v[26:29]
	v_mfma_f32_16x16x32_bf16 v[18:21], v[138:141], v[198:201], v[18:21]
	v_mfma_f32_16x16x32_bf16 v[62:65], v[134:137], v[166:169], v[62:65]
	v_mfma_f32_16x16x32_bf16 v[58:61], v[142:145], v[166:169], v[58:61]
	v_mfma_f32_16x16x32_bf16 v[54:57], v[134:137], v[174:177], v[54:57]
	v_mfma_f32_16x16x32_bf16 v[50:53], v[142:145], v[174:177], v[50:53]
	v_mfma_f32_16x16x32_bf16 v[42:45], v[134:137], v[182:185], v[42:45]
	v_mfma_f32_16x16x32_bf16 v[34:37], v[142:145], v[182:185], v[34:37]
	v_mfma_f32_16x16x32_bf16 v[26:29], v[134:137], v[202:205], v[26:29]
	v_mfma_f32_16x16x32_bf16 v[18:21], v[142:145], v[202:205], v[18:21]
	v_mfma_f32_16x16x32_bf16 v[46:49], v[146:149], v[162:165], v[46:49]
	v_mfma_f32_16x16x32_bf16 v[38:41], v[154:157], v[162:165], v[38:41]
	v_mfma_f32_16x16x32_bf16 v[30:33], v[146:149], v[170:173], v[30:33]
	v_mfma_f32_16x16x32_bf16 v[22:25], v[154:157], v[170:173], v[22:25]
	v_mfma_f32_16x16x32_bf16 v[14:17], v[146:149], v[178:181], v[14:17]
	v_mfma_f32_16x16x32_bf16 v[10:13], v[154:157], v[178:181], v[10:13]
	v_mfma_f32_16x16x32_bf16 v[6:9], v[146:149], v[198:201], v[6:9]
	v_mfma_f32_16x16x32_bf16 v[2:5], v[154:157], v[198:201], v[2:5]
	v_mfma_f32_16x16x32_bf16 v[46:49], v[150:153], v[166:169], v[46:49]
	v_mfma_f32_16x16x32_bf16 v[38:41], v[158:161], v[166:169], v[38:41]
	v_mfma_f32_16x16x32_bf16 v[30:33], v[150:153], v[174:177], v[30:33]
	v_mfma_f32_16x16x32_bf16 v[22:25], v[158:161], v[174:177], v[22:25]
	v_mfma_f32_16x16x32_bf16 v[14:17], v[150:153], v[182:185], v[14:17]
	v_mfma_f32_16x16x32_bf16 v[10:13], v[158:161], v[182:185], v[10:13]
	v_mfma_f32_16x16x32_bf16 v[6:9], v[150:153], v[202:205], v[6:9]
	v_mfma_f32_16x16x32_bf16 v[2:5], v[158:161], v[202:205], v[2:5]
	s_barrier
; #define PG8_STAGE(bufoff, gbase, voff) do { _Pragma("unroll") for (int _i = 0; _i < 2; ++_i) \
;         __builtin_amdgcn_global_load_lds((const unsigned*)((const char*)(gbase) + (voff)[_i]), (PG8_LAS unsigned*)(lds + (bufoff) + ldsw + _i * 8192), 16, 0, 0); } while (0)
; #define PG8_LDA(dst, b, h) do { _Pragma("unroll") for (int m = 0; m < 4; ++m) _Pragma("unroll") for (int k = 0; k < 2; ++k) dst[m][k] = *(const PG8_LAS bf16x8*)(lds + PG8_SA(b, h) + aoff + m * 2048 + k * 1024); } while (0)
; #define PG8_LDB(dst, b, h) do { _Pragma("unroll") for (int n = 0; n < 2; ++n) _Pragma("unroll") for (int k = 0; k < 2; ++k) dst[n][k] = *(const PG8_LAS bf16x8*)(lds + PG8_SB(b, h) + boff + n * 2048 + k * 1024); } while (0)
; #define PG8_MMA(ai, bj, At, Bt) do { __builtin_amdgcn_s_setprio(1); _Pragma("unroll") for (int m = 0; m < 4; ++m) _Pragma("unroll") for (int n = 0; n < 2; ++n) _Pragma("unroll") for (int k = 0; k < 2; ++k) \
;         acc[ai][bj][m][n] = __builtin_amdgcn_mfma_f32_16x16x32_bf16(Bt[n][k], At[m][k], acc[ai][bj][m][n], 0, 0, 0); __builtin_amdgcn_s_setprio(0); } while (0)
; #define PG8_WAIT_V(n) asm volatile("s_waitcnt vmcnt(" #n ")" ::: "memory")
; #define PG8_WAIT_L(n) asm volatile("s_waitcnt lgkmcnt(" #n ")" ::: "memory")
; #define PG8_BAR __builtin_amdgcn_s_barrier()
; #define PG8_SCHED __builtin_amdgcn_sched_barrier(0)
; template <class Epi, class Sched, bool ALIGN_EPI = false, bool SP2 = false>
; __device__ __forceinline__ void gemm_phase(PG8_LAS unsigned char* lds, const Gemm g, const Sched& S, const Epi& E, const int wid) {
;     ...
;             PG8_LDB(B0, 1, 0); PG8_LDB(B1, 1, 1); PG8_SCHED; PG8_LDA(At, 1, 0); PG8_STAGE(PG8_SA(0, 1), a2 + hsA, voffA);
;             PG8_WAIT_V(8); PG8_WAIT_L(0); PG8_BAR; PG8_MMA(0, 0, At, B0); PG8_MMA(0, 1, At, B1); PG8_BAR; PG8_SCHED;
	s_add_i32 s8, 0, 0x18000
	s_add_i32 s9, 0, 0x1c000
	v_add_u32_e32 v142, s8, v229
	v_add_u32_e32 v158, s9, v229
	ds_read_b128 v[130:133], v142
	ds_read_b128 v[134:137], v142 offset:1024
	ds_read_b128 v[138:141], v142 offset:2048
	ds_read_b128 v[142:145], v142 offset:3072
	ds_read_b128 v[146:149], v158
	ds_read_b128 v[150:153], v158 offset:1024
	ds_read_b128 v[154:157], v158 offset:2048
	ds_read_b128 v[158:161], v158 offset:3072
	s_add_u32 s24, s80, 0x40000
	s_addc_u32 s25, s81, 0
	s_mov_b32 m0, s90
	v_lshl_add_u64 v[214:215], s[24:25], 0, v[186:187]
	ds_read_b128 v[162:165], v232 offset:32768
	ds_read_b128 v[166:169], v232 offset:33792
	ds_read_b128 v[170:173], v232 offset:34816
	ds_read_b128 v[174:177], v232 offset:35840
	ds_read_b128 v[178:181], v232 offset:36864
	ds_read_b128 v[182:185], v232 offset:37888
	ds_read_b128 v[198:201], v232 offset:38912
	ds_read_b128 v[202:205], v232 offset:39936
	global_load_lds_dwordx4 v[214:215], off
	v_lshl_add_u64 v[214:215], s[24:25], 0, v[188:189]
	s_mov_b32 m0, s91
	s_nop 0
	global_load_lds_dwordx4 v[214:215], off
	s_waitcnt vmcnt(8)
	s_waitcnt lgkmcnt(0)
	s_barrier
	s_waitcnt lgkmcnt(0)
	v_mfma_f32_16x16x32_bf16 v[126:129], v[130:133], v[162:165], v[126:129]
	v_mfma_f32_16x16x32_bf16 v[122:125], v[138:141], v[162:165], v[122:125]
	v_mfma_f32_16x16x32_bf16 v[118:121], v[130:133], v[170:173], v[118:121]
	v_mfma_f32_16x16x32_bf16 v[114:117], v[138:141], v[170:173], v[114:117]
	v_mfma_f32_16x16x32_bf16 v[106:109], v[130:133], v[178:181], v[106:109]
	v_mfma_f32_16x16x32_bf16 v[98:101], v[138:141], v[178:181], v[98:101]
	v_mfma_f32_16x16x32_bf16 v[90:93], v[130:133], v[198:201], v[90:93]
	v_mfma_f32_16x16x32_bf16 v[82:85], v[138:141], v[198:201], v[82:85]
	v_mfma_f32_16x16x32_bf16 v[126:129], v[134:137], v[166:169], v[126:129]
	v_mfma_f32_16x16x32_bf16 v[122:125], v[142:145], v[166:169], v[122:125]
	v_mfma_f32_16x16x32_bf16 v[118:121], v[134:137], v[174:177], v[118:121]
	v_mfma_f32_16x16x32_bf16 v[114:117], v[142:145], v[174:177], v[114:117]
	v_mfma_f32_16x16x32_bf16 v[106:109], v[134:137], v[182:185], v[106:109]
	v_mfma_f32_16x16x32_bf16 v[98:101], v[142:145], v[182:185], v[98:101]
	v_mfma_f32_16x16x32_bf16 v[90:93], v[134:137], v[202:205], v[90:93]
	v_mfma_f32_16x16x32_bf16 v[82:85], v[142:145], v[202:205], v[82:85]
	v_mfma_f32_16x16x32_bf16 v[110:113], v[146:149], v[162:165], v[110:113]
	v_mfma_f32_16x16x32_bf16 v[102:105], v[154:157], v[162:165], v[102:105]
	v_mfma_f32_16x16x32_bf16 v[94:97], v[146:149], v[170:173], v[94:97]
	v_mfma_f32_16x16x32_bf16 v[86:89], v[154:157], v[170:173], v[86:89]
	v_mfma_f32_16x16x32_bf16 v[78:81], v[146:149], v[178:181], v[78:81]
	v_mfma_f32_16x16x32_bf16 v[74:77], v[154:157], v[178:181], v[74:77]
	v_mfma_f32_16x16x32_bf16 v[70:73], v[146:149], v[198:201], v[70:73]
	v_mfma_f32_16x16x32_bf16 v[66:69], v[154:157], v[198:201], v[66:69]
	v_mfma_f32_16x16x32_bf16 v[110:113], v[150:153], v[166:169], v[110:113]
	v_mfma_f32_16x16x32_bf16 v[102:105], v[158:161], v[166:169], v[102:105]
	v_mfma_f32_16x16x32_bf16 v[94:97], v[150:153], v[174:177], v[94:97]
	v_mfma_f32_16x16x32_bf16 v[86:89], v[158:161], v[174:177], v[86:89]
	v_mfma_f32_16x16x32_bf16 v[78:81], v[150:153], v[182:185], v[78:81]
	v_mfma_f32_16x16x32_bf16 v[74:77], v[158:161], v[182:185], v[74:77]
	v_mfma_f32_16x16x32_bf16 v[70:73], v[150:153], v[202:205], v[70:73]
	v_mfma_f32_16x16x32_bf16 v[66:69], v[158:161], v[202:205], v[66:69]
	s_barrier
; #define PG8_STAGE(bufoff, gbase, voff) do { _Pragma("unroll") for (int _i = 0; _i < 2; ++_i) \
;         __builtin_amdgcn_global_load_lds((const unsigned*)((const char*)(gbase) + (voff)[_i]), (PG8_LAS unsigned*)(lds + (bufoff) + ldsw + _i * 8192), 16, 0, 0); } while (0)
; #define PG8_LDA(dst, b, h) do { _Pragma("unroll") for (int m = 0; m < 4; ++m) _Pragma("unroll") for (int k = 0; k < 2; ++k) dst[m][k] = *(const PG8_LAS bf16x8*)(lds + PG8_SA(b, h) + aoff + m * 2048 + k * 1024); } while (0)
; #define PG8_MMA(ai, bj, At, Bt) do { __builtin_amdgcn_s_setprio(1); _Pragma("unroll") for (int m = 0; m < 4; ++m) _Pragma("unroll") for (int n = 0; n < 2; ++n) _Pragma("unroll") for (int k = 0; k < 2; ++k) \
;         acc[ai][bj][m][n] = __builtin_amdgcn_mfma_f32_16x16x32_bf16(Bt[n][k], At[m][k], acc[ai][bj][m][n], 0, 0, 0); __builtin_amdgcn_s_setprio(0); } while (0)
; #define PG8_WAIT_V(n) asm volatile("s_waitcnt vmcnt(" #n ")" ::: "memory")
; #define PG8_WAIT_L(n) asm volatile("s_waitcnt lgkmcnt(" #n ")" ::: "memory")
; #define PG8_BAR __builtin_amdgcn_s_barrier()
; #define PG8_SCHED __builtin_amdgcn_sched_barrier(0)
; template <class Epi, class Sched, bool ALIGN_EPI = false, bool SP2 = false>
; __device__ __forceinline__ void gemm_phase(PG8_LAS unsigned char* lds, const Gemm g, const Sched& S, const Epi& E, const int wid) {
;     ...
;             PG8_LDA(At, 1, 1); PG8_STAGE(PG8_SB(1, 0), b3, voffB); PG8_STAGE(PG8_SB(1, 1), b3 + hsB, voffB); PG8_STAGE(PG8_SA(1, 0), a3, voffA);
;             PG8_WAIT_V(8); PG8_WAIT_L(0); PG8_BAR; PG8_MMA(1, 0, At, B0); PG8_MMA(1, 1, At, B1); PG8_BAR; PG8_SCHED;
;     ...
;         if constexpr (ALIGN_EPI) { if (wr == 0) PG8_BAR; }
	s_add_i32 s8, s8, s28
	v_lshl_add_u64 v[206:207], v[206:207], 0, s[54:55]
	s_mov_b32 m0, s8
	ds_read_b128 v[162:165], v232 offset:49152
	ds_read_b128 v[166:169], v232 offset:50176
	ds_read_b128 v[170:173], v232 offset:51200
	ds_read_b128 v[174:177], v232 offset:52224
	ds_read_b128 v[178:181], v232 offset:53248
	ds_read_b128 v[182:185], v232 offset:54272
	ds_read_b128 v[198:201], v232 offset:55296
	ds_read_b128 v[202:205], v232 offset:56320
	global_load_lds_dwordx4 v[206:207], off
	s_add_i32 m0, s8, 0x2000
	s_add_u32 s24, s78, 0x40080
	v_lshl_add_u64 v[206:207], v[208:209], 0, s[54:55]
	s_addc_u32 s25, s79, 0
	s_add_i32 s8, s9, s28
	global_load_lds_dwordx4 v[206:207], off
	v_lshl_add_u64 v[206:207], s[24:25], 0, v[186:187]
	s_mov_b32 m0, s8
	s_nop 0
	global_load_lds_dwordx4 v[206:207], off
	v_lshl_add_u64 v[206:207], s[24:25], 0, v[188:189]
	s_add_i32 m0, s8, 0x2000
	s_nop 0
	global_load_lds_dwordx4 v[206:207], off
	v_lshl_add_u64 v[206:207], v[210:211], 0, s[54:55]
	s_mov_b32 m0, s19
	s_nop 0
	global_load_lds_dwordx4 v[206:207], off
	v_lshl_add_u64 v[206:207], v[212:213], 0, s[54:55]
	s_mov_b32 m0, s42
	s_nop 0
	global_load_lds_dwordx4 v[206:207], off
	s_waitcnt vmcnt(8)
	s_waitcnt lgkmcnt(0)
	s_barrier
	s_waitcnt lgkmcnt(0)
	v_mfma_f32_16x16x32_bf16 v[62:65], v[130:133], v[162:165], v[62:65]
	v_mfma_f32_16x16x32_bf16 v[58:61], v[138:141], v[162:165], v[58:61]
	v_mfma_f32_16x16x32_bf16 v[54:57], v[130:133], v[170:173], v[54:57]
	v_mfma_f32_16x16x32_bf16 v[50:53], v[138:141], v[170:173], v[50:53]
	v_mfma_f32_16x16x32_bf16 v[42:45], v[130:133], v[178:181], v[42:45]
	v_mfma_f32_16x16x32_bf16 v[34:37], v[138:141], v[178:181], v[34:37]
	v_mfma_f32_16x16x32_bf16 v[26:29], v[130:133], v[198:201], v[26:29]
	v_mfma_f32_16x16x32_bf16 v[18:21], v[138:141], v[198:201], v[18:21]
	v_mfma_f32_16x16x32_bf16 v[62:65], v[134:137], v[166:169], v[62:65]
	v_mfma_f32_16x16x32_bf16 v[58:61], v[142:145], v[166:169], v[58:61]
	v_mfma_f32_16x16x32_bf16 v[54:57], v[134:137], v[174:177], v[54:57]
	v_mfma_f32_16x16x32_bf16 v[50:53], v[142:145], v[174:177], v[50:53]
	v_mfma_f32_16x16x32_bf16 v[42:45], v[134:137], v[182:185], v[42:45]
	v_mfma_f32_16x16x32_bf16 v[34:37], v[142:145], v[182:185], v[34:37]
	v_mfma_f32_16x16x32_bf16 v[26:29], v[134:137], v[202:205], v[26:29]
	v_mfma_f32_16x16x32_bf16 v[18:21], v[142:145], v[202:205], v[18:21]
	v_mfma_f32_16x16x32_bf16 v[46:49], v[146:149], v[162:165], v[46:49]
	v_mfma_f32_16x16x32_bf16 v[38:41], v[154:157], v[162:165], v[38:41]
	v_mfma_f32_16x16x32_bf16 v[30:33], v[146:149], v[170:173], v[30:33]
	v_mfma_f32_16x16x32_bf16 v[22:25], v[154:157], v[170:173], v[22:25]
	v_mfma_f32_16x16x32_bf16 v[14:17], v[146:149], v[178:181], v[14:17]
	v_mfma_f32_16x16x32_bf16 v[10:13], v[154:157], v[178:181], v[10:13]
	v_mfma_f32_16x16x32_bf16 v[6:9], v[146:149], v[198:201], v[6:9]
	v_mfma_f32_16x16x32_bf16 v[2:5], v[154:157], v[198:201], v[2:5]
	v_mfma_f32_16x16x32_bf16 v[46:49], v[150:153], v[166:169], v[46:49]
	v_mfma_f32_16x16x32_bf16 v[38:41], v[158:161], v[166:169], v[38:41]
	v_mfma_f32_16x16x32_bf16 v[30:33], v[150:153], v[174:177], v[30:33]
	v_mfma_f32_16x16x32_bf16 v[22:25], v[158:161], v[174:177], v[22:25]
	v_mfma_f32_16x16x32_bf16 v[14:17], v[150:153], v[182:185], v[14:17]
	v_mfma_f32_16x16x32_bf16 v[10:13], v[158:161], v[182:185], v[10:13]
	v_mfma_f32_16x16x32_bf16 v[6:9], v[150:153], v[202:205], v[6:9]
	v_mfma_f32_16x16x32_bf16 v[2:5], v[158:161], v[202:205], v[2:5]
	s_barrier
	s_add_u32 s12, s12, 0x100
	s_addc_u32 s13, s13, 0
	s_add_u32 s83, s83, 0x100
	s_addc_u32 vcc_lo, vcc_lo, 0
	s_cmp_ge_u32 vcc_hi, s77
	s_mov_b32 s80, vcc_hi
	s_cbranch_scc0 .LBB0_1281
	s_setprio 0
	s_and_b64 vcc, exec, s[6:7]
	s_cbranch_vccz .LBB0_1284
	s_barrier

;     __device__ __forceinline__ const char* a_ptr(const Gemm& g, const Unit& u, size_t tsA) const { return (const char*)g.A + (size_t)u.pm * tsA + (size_t)u.pn * g.a_pn_bytes + (u.ks > 0 ? (size_t)u.ks * g.ks_bytes : 0); }
;     __device__ __forceinline__ const char* b_ptr(const Gemm& g, const Unit& u, size_t tsB) const { return (const char*)g.Bt + (size_t)u.pn * tsB + (u.ks > 0 ? (size_t)u.ks * g.ks_bytes : 0); }
;     __device__ __forceinline__ const char* a_ptr(const Gemm& g, const Unit& u, size_t tsA) const { return (const char*)g.A + (size_t)u.pm * tsA + (size_t)u.pn * g.a_pn_bytes + (u.ks > 0 ? (size_t)u.ks * g.ks_bytes : 0); }
;     __device__ __forceinline__ const char* b_ptr(const Gemm& g, const Unit& u, size_t tsB) const { return (const char*)g.Bt + (size_t)u.pn * tsB + (u.ks > 0 ? (size_t)u.ks * g.ks_bytes : 0); }
; #define PG8_WAIT_V(n) asm volatile("s_waitcnt vmcnt(" #n ")" ::: "memory")
; template <class Epi, class Sched, bool ALIGN_EPI = false, bool SP2 = false>
; __device__ __forceinline__ void gemm_phase(PG8_LAS unsigned char* lds, const Gemm g, const Sched& S, const Epi& E, const int wid) {
;     ...
;         const bool has_next = S.next(ui + 1, nxt);
;         const char* nA = has_next ? S.a_ptr(g, nxt, tsA) : cA; const char* nB = has_next ? S.b_ptr(g, nxt, tsB) : cB;
;         const int nt = cur.ks >= 0 ? g.nt_split : ntfull;
; #pragma unroll 1
;         for (int t = 0; t < nt; t += 2) {
;             const bool last = (t == nt - 2);
;             const char* a1 = cA + (size_t)(t + 1) * kstep;
;             const char* a2 = last ? nA : cA + (size_t)(t + 2) * kstep; const char* b2 = last ? nB : cB + (size_t)(t + 2) * kstep;
;             const char* a3 = a2 + kstep; const char* b3 = b2 + kstep;
;             if (last && has_next) S.a_ready(nxt);
;             if constexpr (SP2) {
;             PG8_LDB(B0, 0, 0); PG8_LDB(B1, 0, 1); PG8_SCHED; PG8_LDA(At, 0, 0); PG8_STAGE(PG8_SA(1, 1), a1 + hsA, voffA);
;             PG8_WAIT_V(8); PG8_WAIT_L(0); PG8_BAR; PG8_MMA(0, 0, At, B0); PG8_MMA(0, 1, At, B1); PG8_BAR; PG8_SCHED;
;     ...
; #pragma unroll
;         for (int a = 0; a < 2; ++a)
; #pragma unroll
;             for (int b = 0; b < 2; ++b)
; #pragma unroll
;                 for (int m = 0; m < 4; ++m)
; #pragma unroll
;                     for (int n = 0; n < 2; ++n) acc[a][b][m][n] = (f32x4){0.f, 0.f, 0.f, 0.f};
.LBB0_1473:
	s_ashr_i32 s49, s48, 31
	s_lshl_b64 s[24:25], s[48:49], 19
	s_add_u32 s50, s3, s24
	s_addc_u32 s51, s4, s25
	s_and_b64 s[24:25], s[12:13], exec
	s_cselect_b32 s49, s51, s57
	s_cselect_b32 s65, s50, s56
	s_ashr_i32 s47, s46, 31
	s_lshl_b64 s[24:25], s[46:47], 19
	s_add_u32 s52, s5, s24
	s_addc_u32 s53, s10, s25
	s_and_b64 s[24:25], s[12:13], exec
	s_cselect_b32 s47, s53, s59
	s_cselect_b32 s66, s52, s58
	s_add_u32 s56, s56, 0x40080
	s_addc_u32 s57, s57, 0
	s_add_u32 s67, s58, 0x100
	v_mov_b32_e32 v2, 0
	s_addc_u32 s68, s59, 0
	s_mov_b32 s69, -2
	v_mov_b32_e32 v3, v2
	v_mov_b32_e32 v4, v2
	v_mov_b32_e32 v5, v2
	v_mov_b32_e32 v6, v2
	v_mov_b32_e32 v7, v2
	v_mov_b32_e32 v8, v2
	v_mov_b32_e32 v9, v2
	v_mov_b32_e32 v18, v2
	v_mov_b32_e32 v19, v2
	v_mov_b32_e32 v20, v2
	v_mov_b32_e32 v21, v2
	v_mov_b32_e32 v22, v2
	v_mov_b32_e32 v23, v2
	v_mov_b32_e32 v24, v2
	v_mov_b32_e32 v25, v2
	v_mov_b32_e32 v34, v2
	v_mov_b32_e32 v35, v2
	v_mov_b32_e32 v36, v2
	v_mov_b32_e32 v37, v2
	v_mov_b32_e32 v38, v2
	v_mov_b32_e32 v39, v2
	v_mov_b32_e32 v40, v2
	v_mov_b32_e32 v41, v2
	v_mov_b32_e32 v50, v2
	v_mov_b32_e32 v51, v2
	v_mov_b32_e32 v52, v2
	v_mov_b32_e32 v53, v2
	v_mov_b32_e32 v54, v2
	v_mov_b32_e32 v55, v2
	v_mov_b32_e32 v56, v2
	v_mov_b32_e32 v57, v2
	v_mov_b32_e32 v10, v2
	v_mov_b32_e32 v11, v2
	v_mov_b32_e32 v12, v2
	v_mov_b32_e32 v13, v2
	v_mov_b32_e32 v14, v2
	v_mov_b32_e32 v15, v2
	v_mov_b32_e32 v16, v2
	v_mov_b32_e32 v17, v2
	v_mov_b32_e32 v26, v2
	v_mov_b32_e32 v27, v2
	v_mov_b32_e32 v28, v2
	v_mov_b32_e32 v29, v2
	v_mov_b32_e32 v30, v2
	v_mov_b32_e32 v31, v2
	v_mov_b32_e32 v32, v2
	v_mov_b32_e32 v33, v2
	v_mov_b32_e32 v42, v2
	v_mov_b32_e32 v43, v2
	v_mov_b32_e32 v44, v2
	v_mov_b32_e32 v45, v2
	v_mov_b32_e32 v46, v2
	v_mov_b32_e32 v47, v2
	v_mov_b32_e32 v48, v2
	v_mov_b32_e32 v49, v2
	v_mov_b32_e32 v58, v2
	v_mov_b32_e32 v59, v2
	v_mov_b32_e32 v60, v2
	v_mov_b32_e32 v61, v2
	v_mov_b32_e32 v62, v2
	v_mov_b32_e32 v63, v2
	v_mov_b32_e32 v64, v2
	v_mov_b32_e32 v65, v2
	v_mov_b32_e32 v66, v2
	v_mov_b32_e32 v67, v2
	v_mov_b32_e32 v68, v2
	v_mov_b32_e32 v69, v2
	v_mov_b32_e32 v70, v2
	v_mov_b32_e32 v71, v2
	v_mov_b32_e32 v72, v2
	v_mov_b32_e32 v73, v2
	v_mov_b32_e32 v82, v2
	v_mov_b32_e32 v83, v2
	v_mov_b32_e32 v84, v2
	v_mov_b32_e32 v85, v2
	v_mov_b32_e32 v86, v2
	v_mov_b32_e32 v87, v2
	v_mov_b32_e32 v88, v2
	v_mov_b32_e32 v89, v2
	v_mov_b32_e32 v98, v2
	v_mov_b32_e32 v99, v2
	v_mov_b32_e32 v100, v2
	v_mov_b32_e32 v101, v2
	v_mov_b32_e32 v102, v2
	v_mov_b32_e32 v103, v2
	v_mov_b32_e32 v104, v2
	v_mov_b32_e32 v105, v2
	v_mov_b32_e32 v114, v2
	v_mov_b32_e32 v115, v2
	v_mov_b32_e32 v116, v2
	v_mov_b32_e32 v117, v2
	v_mov_b32_e32 v118, v2
	v_mov_b32_e32 v119, v2
	v_mov_b32_e32 v120, v2
	v_mov_b32_e32 v121, v2
	v_mov_b32_e32 v74, v2
	v_mov_b32_e32 v75, v2
	v_mov_b32_e32 v76, v2
	v_mov_b32_e32 v77, v2
	v_mov_b32_e32 v78, v2
	v_mov_b32_e32 v79, v2
	v_mov_b32_e32 v80, v2
	v_mov_b32_e32 v81, v2
	v_mov_b32_e32 v90, v2
	v_mov_b32_e32 v91, v2
	v_mov_b32_e32 v92, v2
	v_mov_b32_e32 v93, v2
	v_mov_b32_e32 v94, v2
	v_mov_b32_e32 v95, v2
	v_mov_b32_e32 v96, v2
	v_mov_b32_e32 v97, v2
	v_mov_b32_e32 v106, v2
	v_mov_b32_e32 v107, v2
	v_mov_b32_e32 v108, v2
	v_mov_b32_e32 v109, v2
	v_mov_b32_e32 v110, v2
	v_mov_b32_e32 v111, v2
	v_mov_b32_e32 v112, v2
	v_mov_b32_e32 v113, v2
	v_mov_b32_e32 v122, v2
	v_mov_b32_e32 v123, v2
	v_mov_b32_e32 v124, v2
	v_mov_b32_e32 v125, v2
	v_mov_b32_e32 v126, v2
	v_mov_b32_e32 v127, v2
	v_mov_b32_e32 v128, v2
	v_mov_b32_e32 v129, v2
	s_cmp_lg_u64 s[6:7], 0
	s_cbranch_scc1 .Lsprio2
	s_setprio 1
.Lsprio2:
	s_cmp_eq_u32 s26, 1
	s_cbranch_scc1 .LBB0_1474
.Lp9_peel:
	ds_read_b128 v[152:155], v149
	ds_read_b128 v[156:159], v149 offset:1024
	ds_read_b128 v[160:163], v149 offset:2048
	ds_read_b128 v[164:167], v149 offset:3072
	ds_read_b128 v[168:171], v150
	ds_read_b128 v[172:175], v150 offset:1024
	ds_read_b128 v[176:179], v150 offset:2048
	ds_read_b128 v[180:183], v150 offset:3072
	s_add_u32 s8, s56, 0xfffc0080
	s_addc_u32 s9, s57, -1
	s_cmp_eq_u32 s69, 12
	s_cselect_b32 s61, s49, s9
	s_cselect_b32 s60, s65, s8
	s_cselect_b32 s59, s47, s68
	s_cselect_b32 s58, s66, s67
	v_lshl_add_u64 v[146:147], s[56:57], 0, v[138:139]
	s_add_i32 m0, s85, 0xc000
	ds_read_b128 v[184:187], v151
	ds_read_b128 v[188:191], v151 offset:1024
	ds_read_b128 v[192:195], v151 offset:2048
	ds_read_b128 v[196:199], v151 offset:3072
	ds_read_b128 v[200:203], v151 offset:4096
	ds_read_b128 v[204:207], v151 offset:5120
	ds_read_b128 v[208:211], v151 offset:6144
	ds_read_b128 v[212:215], v151 offset:7168
	v_lshl_add_u64 v[146:147], s[56:57], 0, v[140:141]
	s_add_i32 m0, s85, 0xe000
	s_nop 0
	s_waitcnt vmcnt(24)
	s_waitcnt lgkmcnt(0)
	s_barrier
; #define PG8_STAGE(bufoff, gbase, voff) do { _Pragma("unroll") for (int _i = 0; _i < 2; ++_i) \
;         __builtin_amdgcn_global_load_lds((const unsigned*)((const char*)(gbase) + (voff)[_i]), (PG8_LAS unsigned*)(lds + (bufoff) + ldsw + _i * 8192), 16, 0, 0); } while (0)
; #define PG8_LDA(dst, b, h) do { _Pragma("unroll") for (int m = 0; m < 4; ++m) _Pragma("unroll") for (int k = 0; k < 2; ++k) dst[m][k] = *(const PG8_LAS bf16x8*)(lds + PG8_SA(b, h) + aoff + m * 2048 + k * 1024); } while (0)
; #define PG8_MMA(ai, bj, At, Bt) do { __builtin_amdgcn_s_setprio(1); _Pragma("unroll") for (int m = 0; m < 4; ++m) _Pragma("unroll") for (int n = 0; n < 2; ++n) _Pragma("unroll") for (int k = 0; k < 2; ++k) \
;         acc[ai][bj][m][n] = __builtin_amdgcn_mfma_f32_16x16x32_bf16(Bt[n][k], At[m][k], acc[ai][bj][m][n], 0, 0, 0); __builtin_amdgcn_s_setprio(0); } while (0)
; #define PG8_WAIT_V(n) asm volatile("s_waitcnt vmcnt(" #n ")" ::: "memory")
; #define PG8_WAIT_L(n) asm volatile("s_waitcnt lgkmcnt(" #n ")" ::: "memory")
; #define PG8_BAR __builtin_amdgcn_s_barrier()
; #define PG8_SCHED __builtin_amdgcn_sched_barrier(0)
; template <class Epi, class Sched, bool ALIGN_EPI = false, bool SP2 = false>
; __device__ __forceinline__ void gemm_phase(PG8_LAS unsigned char* lds, const Gemm g, const Sched& S, const Epi& E, const int wid) {
;     ...
;             PG8_WAIT_V(8); PG8_WAIT_L(0); PG8_BAR; PG8_MMA(0, 0, At, B0); PG8_MMA(0, 1, At, B1); PG8_BAR; PG8_SCHED;
;             PG8_LDA(At, 0, 1); PG8_STAGE(PG8_SB(0, 0), b2, voffB); PG8_STAGE(PG8_SB(0, 1), b2 + hsB, voffB); PG8_STAGE(PG8_SA(0, 0), a2, voffA);
;             PG8_WAIT_V(8); PG8_WAIT_L(0); PG8_BAR; PG8_MMA(1, 0, At, B0); PG8_MMA(1, 1, At, B1); PG8_BAR; PG8_SCHED;
	s_waitcnt lgkmcnt(0)
	v_mfma_f32_16x16x32_bf16 v[126:129], v[152:155], v[184:187], v[126:129]
	v_mfma_f32_16x16x32_bf16 v[122:125], v[160:163], v[184:187], v[122:125]
	v_mfma_f32_16x16x32_bf16 v[110:113], v[152:155], v[192:195], v[110:113]
	v_mfma_f32_16x16x32_bf16 v[106:109], v[160:163], v[192:195], v[106:109]
	v_mfma_f32_16x16x32_bf16 v[94:97], v[152:155], v[200:203], v[94:97]
	v_mfma_f32_16x16x32_bf16 v[90:93], v[160:163], v[200:203], v[90:93]
	v_mfma_f32_16x16x32_bf16 v[78:81], v[152:155], v[208:211], v[78:81]
	v_mfma_f32_16x16x32_bf16 v[74:77], v[160:163], v[208:211], v[74:77]
	v_mfma_f32_16x16x32_bf16 v[126:129], v[156:159], v[188:191], v[126:129]
	v_mfma_f32_16x16x32_bf16 v[122:125], v[164:167], v[188:191], v[122:125]
	v_mfma_f32_16x16x32_bf16 v[110:113], v[156:159], v[196:199], v[110:113]
	v_mfma_f32_16x16x32_bf16 v[106:109], v[164:167], v[196:199], v[106:109]
	v_mfma_f32_16x16x32_bf16 v[94:97], v[156:159], v[204:207], v[94:97]
	v_mfma_f32_16x16x32_bf16 v[90:93], v[164:167], v[204:207], v[90:93]
	v_mfma_f32_16x16x32_bf16 v[78:81], v[156:159], v[212:215], v[78:81]
	v_mfma_f32_16x16x32_bf16 v[74:77], v[164:167], v[212:215], v[74:77]
	v_mfma_f32_16x16x32_bf16 v[118:121], v[168:171], v[184:187], v[118:121]
	v_mfma_f32_16x16x32_bf16 v[114:117], v[176:179], v[184:187], v[114:117]
	v_mfma_f32_16x16x32_bf16 v[102:105], v[168:171], v[192:195], v[102:105]
	v_mfma_f32_16x16x32_bf16 v[98:101], v[176:179], v[192:195], v[98:101]
	v_mfma_f32_16x16x32_bf16 v[86:89], v[168:171], v[200:203], v[86:89]
	v_mfma_f32_16x16x32_bf16 v[82:85], v[176:179], v[200:203], v[82:85]
	v_mfma_f32_16x16x32_bf16 v[70:73], v[168:171], v[208:211], v[70:73]
	v_mfma_f32_16x16x32_bf16 v[66:69], v[176:179], v[208:211], v[66:69]
	v_mfma_f32_16x16x32_bf16 v[118:121], v[172:175], v[188:191], v[118:121]
	v_mfma_f32_16x16x32_bf16 v[114:117], v[180:183], v[188:191], v[114:117]
	v_mfma_f32_16x16x32_bf16 v[102:105], v[172:175], v[196:199], v[102:105]
	v_mfma_f32_16x16x32_bf16 v[98:101], v[180:183], v[196:199], v[98:101]
	v_mfma_f32_16x16x32_bf16 v[86:89], v[172:175], v[204:207], v[86:89]
	v_mfma_f32_16x16x32_bf16 v[82:85], v[180:183], v[204:207], v[82:85]
	v_mfma_f32_16x16x32_bf16 v[70:73], v[172:175], v[212:215], v[70:73]
	v_mfma_f32_16x16x32_bf16 v[66:69], v[180:183], v[212:215], v[66:69]
	s_barrier
	s_add_i32 s8, s35, s28
	v_lshl_add_u64 v[146:147], s[58:59], 0, v[134:135]
	s_mov_b32 m0, s8
	ds_read_b128 v[184:187], v151 offset:16384
	ds_read_b128 v[188:191], v151 offset:17408
	ds_read_b128 v[192:195], v151 offset:18432
	ds_read_b128 v[196:199], v151 offset:19456
	ds_read_b128 v[200:203], v151 offset:20480
	ds_read_b128 v[204:207], v151 offset:21504
	ds_read_b128 v[208:211], v151 offset:22528
	ds_read_b128 v[212:215], v151 offset:23552
	global_load_lds_dwordx4 v[146:147], off
	s_add_i32 m0, s8, 0x2000
	s_add_u32 s24, s58, 0x40000
	v_lshl_add_u64 v[216:217], s[58:59], 0, v[130:131]
	s_addc_u32 s25, s59, 0
	s_add_i32 s8, s36, s28
	global_load_lds_dwordx4 v[216:217], off
	v_lshl_add_u64 v[218:219], s[24:25], 0, v[134:135]
	s_mov_b32 m0, s8
	v_lshl_add_u64 v[220:221], s[60:61], 0, v[132:133]
	global_load_lds_dwordx4 v[218:219], off
	v_lshl_add_u64 v[218:219], s[24:25], 0, v[130:131]
	s_add_i32 m0, s8, 0x2000
	s_nop 0
	global_load_lds_dwordx4 v[218:219], off
	v_lshl_add_u64 v[218:219], s[60:61], 0, v[136:137]
	s_mov_b32 m0, s85
	s_nop 0
	global_load_lds_dwordx4 v[218:219], off
	s_mov_b32 m0, s17
	s_nop 0
	global_load_lds_dwordx4 v[220:221], off
	s_waitcnt vmcnt(24)
	s_waitcnt lgkmcnt(0)
	s_barrier
	s_waitcnt lgkmcnt(0)
	v_mfma_f32_16x16x32_bf16 v[62:65], v[152:155], v[184:187], v[62:65]
	v_mfma_f32_16x16x32_bf16 v[58:61], v[160:163], v[184:187], v[58:61]
	v_mfma_f32_16x16x32_bf16 v[46:49], v[152:155], v[192:195], v[46:49]
	v_mfma_f32_16x16x32_bf16 v[42:45], v[160:163], v[192:195], v[42:45]
	v_mfma_f32_16x16x32_bf16 v[30:33], v[152:155], v[200:203], v[30:33]
	v_mfma_f32_16x16x32_bf16 v[26:29], v[160:163], v[200:203], v[26:29]
	v_mfma_f32_16x16x32_bf16 v[14:17], v[152:155], v[208:211], v[14:17]
	v_mfma_f32_16x16x32_bf16 v[10:13], v[160:163], v[208:211], v[10:13]
	v_mfma_f32_16x16x32_bf16 v[62:65], v[156:159], v[188:191], v[62:65]
	v_mfma_f32_16x16x32_bf16 v[58:61], v[164:167], v[188:191], v[58:61]
	v_mfma_f32_16x16x32_bf16 v[46:49], v[156:159], v[196:199], v[46:49]
	v_mfma_f32_16x16x32_bf16 v[42:45], v[164:167], v[196:199], v[42:45]
	v_mfma_f32_16x16x32_bf16 v[30:33], v[156:159], v[204:207], v[30:33]
	v_mfma_f32_16x16x32_bf16 v[26:29], v[164:167], v[204:207], v[26:29]
	v_mfma_f32_16x16x32_bf16 v[14:17], v[156:159], v[212:215], v[14:17]
	v_mfma_f32_16x16x32_bf16 v[10:13], v[164:167], v[212:215], v[10:13]
	v_mfma_f32_16x16x32_bf16 v[54:57], v[168:171], v[184:187], v[54:57]
	v_mfma_f32_16x16x32_bf16 v[50:53], v[176:179], v[184:187], v[50:53]
	v_mfma_f32_16x16x32_bf16 v[38:41], v[168:171], v[192:195], v[38:41]
	v_mfma_f32_16x16x32_bf16 v[34:37], v[176:179], v[192:195], v[34:37]
	v_mfma_f32_16x16x32_bf16 v[22:25], v[168:171], v[200:203], v[22:25]
	v_mfma_f32_16x16x32_bf16 v[18:21], v[176:179], v[200:203], v[18:21]
	v_mfma_f32_16x16x32_bf16 v[6:9], v[168:171], v[208:211], v[6:9]
	v_mfma_f32_16x16x32_bf16 v[2:5], v[176:179], v[208:211], v[2:5]
	v_mfma_f32_16x16x32_bf16 v[54:57], v[172:175], v[188:191], v[54:57]
	v_mfma_f32_16x16x32_bf16 v[50:53], v[180:183], v[188:191], v[50:53]
	v_mfma_f32_16x16x32_bf16 v[38:41], v[172:175], v[196:199], v[38:41]
	v_mfma_f32_16x16x32_bf16 v[34:37], v[180:183], v[196:199], v[34:37]
	v_mfma_f32_16x16x32_bf16 v[22:25], v[172:175], v[204:207], v[22:25]
	v_mfma_f32_16x16x32_bf16 v[18:21], v[180:183], v[204:207], v[18:21]
	v_mfma_f32_16x16x32_bf16 v[6:9], v[172:175], v[212:215], v[6:9]
	v_mfma_f32_16x16x32_bf16 v[2:5], v[180:183], v[212:215], v[2:5]
	s_barrier
; #define PG8_STAGE(bufoff, gbase, voff) do { _Pragma("unroll") for (int _i = 0; _i < 2; ++_i) \
;         __builtin_amdgcn_global_load_lds((const unsigned*)((const char*)(gbase) + (voff)[_i]), (PG8_LAS unsigned*)(lds + (bufoff) + ldsw + _i * 8192), 16, 0, 0); } while (0)
; #define PG8_LDA(dst, b, h) do { _Pragma("unroll") for (int m = 0; m < 4; ++m) _Pragma("unroll") for (int k = 0; k < 2; ++k) dst[m][k] = *(const PG8_LAS bf16x8*)(lds + PG8_SA(b, h) + aoff + m * 2048 + k * 1024); } while (0)
; #define PG8_LDB(dst, b, h) do { _Pragma("unroll") for (int n = 0; n < 2; ++n) _Pragma("unroll") for (int k = 0; k < 2; ++k) dst[n][k] = *(const PG8_LAS bf16x8*)(lds + PG8_SB(b, h) + boff + n * 2048 + k * 1024); } while (0)
; #define PG8_MMA(ai, bj, At, Bt) do { __builtin_amdgcn_s_setprio(1); _Pragma("unroll") for (int m = 0; m < 4; ++m) _Pragma("unroll") for (int n = 0; n < 2; ++n) _Pragma("unroll") for (int k = 0; k < 2; ++k) \
;         acc[ai][bj][m][n] = __builtin_amdgcn_mfma_f32_16x16x32_bf16(Bt[n][k], At[m][k], acc[ai][bj][m][n], 0, 0, 0); __builtin_amdgcn_s_setprio(0); } while (0)
; #define PG8_WAIT_V(n) asm volatile("s_waitcnt vmcnt(" #n ")" ::: "memory")
; #define PG8_WAIT_L(n) asm volatile("s_waitcnt lgkmcnt(" #n ")" ::: "memory")
; #define PG8_BAR __builtin_amdgcn_s_barrier()
; #define PG8_SCHED __builtin_amdgcn_sched_barrier(0)
; template <class Epi, class Sched, bool ALIGN_EPI = false, bool SP2 = false>
; __device__ __forceinline__ void gemm_phase(PG8_LAS unsigned char* lds, const Gemm g, const Sched& S, const Epi& E, const int wid) {
;     ...
;             PG8_LDB(B0, 1, 0); PG8_LDB(B1, 1, 1); PG8_SCHED; PG8_LDA(At, 1, 0); PG8_STAGE(PG8_SA(0, 1), a2 + hsA, voffA);
;             PG8_WAIT_V(8); PG8_WAIT_L(0); PG8_BAR; PG8_MMA(0, 0, At, B0); PG8_MMA(0, 1, At, B1); PG8_BAR; PG8_SCHED;
;             PG8_LDA(At, 1, 1); PG8_STAGE(PG8_SB(1, 0), b3, voffB); PG8_STAGE(PG8_SB(1, 1), b3 + hsB, voffB); PG8_STAGE(PG8_SA(1, 0), a3, voffA);
;             PG8_WAIT_V(8); PG8_WAIT_L(0); PG8_BAR; PG8_MMA(1, 0, At, B0); PG8_MMA(1, 1, At, B1); PG8_BAR; PG8_SCHED;
	s_add_i32 s8, 0, 0x18000
	s_add_i32 s9, 0, 0x1c000
	v_add_u32_e32 v164, s8, v148
	v_add_u32_e32 v180, s9, v148
	ds_read_b128 v[152:155], v164
	ds_read_b128 v[156:159], v164 offset:1024
	ds_read_b128 v[160:163], v164 offset:2048
	ds_read_b128 v[164:167], v164 offset:3072
	ds_read_b128 v[168:171], v180
	ds_read_b128 v[172:175], v180 offset:1024
	ds_read_b128 v[176:179], v180 offset:2048
	ds_read_b128 v[180:183], v180 offset:3072
	s_add_u32 s24, s60, 0x40000
	s_addc_u32 s25, s61, 0
	s_mov_b32 m0, s18
	v_lshl_add_u64 v[222:223], s[24:25], 0, v[136:137]
	ds_read_b128 v[184:187], v151 offset:32768
	ds_read_b128 v[188:191], v151 offset:33792
	ds_read_b128 v[192:195], v151 offset:34816
	ds_read_b128 v[196:199], v151 offset:35840
	ds_read_b128 v[200:203], v151 offset:36864
	ds_read_b128 v[204:207], v151 offset:37888
	ds_read_b128 v[208:211], v151 offset:38912
	ds_read_b128 v[212:215], v151 offset:39936
	global_load_lds_dwordx4 v[222:223], off
	v_lshl_add_u64 v[222:223], s[24:25], 0, v[132:133]
	s_mov_b32 m0, s19
	s_nop 0
	global_load_lds_dwordx4 v[222:223], off
	s_waitcnt vmcnt(24)
	s_waitcnt lgkmcnt(0)
	s_barrier
	s_waitcnt lgkmcnt(0)
	v_mfma_f32_16x16x32_bf16 v[126:129], v[152:155], v[184:187], v[126:129]
	v_mfma_f32_16x16x32_bf16 v[122:125], v[160:163], v[184:187], v[122:125]
	v_mfma_f32_16x16x32_bf16 v[110:113], v[152:155], v[192:195], v[110:113]
	v_mfma_f32_16x16x32_bf16 v[106:109], v[160:163], v[192:195], v[106:109]
	v_mfma_f32_16x16x32_bf16 v[94:97], v[152:155], v[200:203], v[94:97]
	v_mfma_f32_16x16x32_bf16 v[90:93], v[160:163], v[200:203], v[90:93]
	v_mfma_f32_16x16x32_bf16 v[78:81], v[152:155], v[208:211], v[78:81]
	v_mfma_f32_16x16x32_bf16 v[74:77], v[160:163], v[208:211], v[74:77]
	v_mfma_f32_16x16x32_bf16 v[126:129], v[156:159], v[188:191], v[126:129]
	v_mfma_f32_16x16x32_bf16 v[122:125], v[164:167], v[188:191], v[122:125]
	v_mfma_f32_16x16x32_bf16 v[110:113], v[156:159], v[196:199], v[110:113]
	v_mfma_f32_16x16x32_bf16 v[106:109], v[164:167], v[196:199], v[106:109]
	v_mfma_f32_16x16x32_bf16 v[94:97], v[156:159], v[204:207], v[94:97]
	v_mfma_f32_16x16x32_bf16 v[90:93], v[164:167], v[204:207], v[90:93]
	v_mfma_f32_16x16x32_bf16 v[78:81], v[156:159], v[212:215], v[78:81]
	v_mfma_f32_16x16x32_bf16 v[74:77], v[164:167], v[212:215], v[74:77]
	v_mfma_f32_16x16x32_bf16 v[118:121], v[168:171], v[184:187], v[118:121]
	v_mfma_f32_16x16x32_bf16 v[114:117], v[176:179], v[184:187], v[114:117]
	v_mfma_f32_16x16x32_bf16 v[102:105], v[168:171], v[192:195], v[102:105]
	v_mfma_f32_16x16x32_bf16 v[98:101], v[176:179], v[192:195], v[98:101]
	v_mfma_f32_16x16x32_bf16 v[86:89], v[168:171], v[200:203], v[86:89]
	v_mfma_f32_16x16x32_bf16 v[82:85], v[176:179], v[200:203], v[82:85]
	v_mfma_f32_16x16x32_bf16 v[70:73], v[168:171], v[208:211], v[70:73]
	v_mfma_f32_16x16x32_bf16 v[66:69], v[176:179], v[208:211], v[66:69]
	v_mfma_f32_16x16x32_bf16 v[118:121], v[172:175], v[188:191], v[118:121]
	v_mfma_f32_16x16x32_bf16 v[114:117], v[180:183], v[188:191], v[114:117]
	v_mfma_f32_16x16x32_bf16 v[102:105], v[172:175], v[196:199], v[102:105]
	v_mfma_f32_16x16x32_bf16 v[98:101], v[180:183], v[196:199], v[98:101]
	v_mfma_f32_16x16x32_bf16 v[86:89], v[172:175], v[204:207], v[86:89]
	v_mfma_f32_16x16x32_bf16 v[82:85], v[180:183], v[204:207], v[82:85]
	v_mfma_f32_16x16x32_bf16 v[70:73], v[172:175], v[212:215], v[70:73]
	v_mfma_f32_16x16x32_bf16 v[66:69], v[180:183], v[212:215], v[66:69]
	s_barrier
	s_add_i32 s8, s8, s28
	v_lshl_add_u64 v[146:147], v[146:147], 0, s[20:21]
	s_mov_b32 m0, s8
	ds_read_b128 v[184:187], v151 offset:49152
	ds_read_b128 v[188:191], v151 offset:50176
	ds_read_b128 v[192:195], v151 offset:51200
	ds_read_b128 v[196:199], v151 offset:52224
	ds_read_b128 v[200:203], v151 offset:53248
	ds_read_b128 v[204:207], v151 offset:54272
	ds_read_b128 v[208:211], v151 offset:55296
	ds_read_b128 v[212:215], v151 offset:56320
	global_load_lds_dwordx4 v[146:147], off
	s_add_i32 m0, s8, 0x2000
	s_add_u32 s24, s58, 0x40080
	v_lshl_add_u64 v[146:147], v[216:217], 0, s[20:21]
	s_addc_u32 s25, s59, 0
	s_add_i32 s8, s9, s28
	global_load_lds_dwordx4 v[146:147], off
	v_lshl_add_u64 v[146:147], s[24:25], 0, v[134:135]
	s_mov_b32 m0, s8
	s_nop 0
	global_load_lds_dwordx4 v[146:147], off
	v_lshl_add_u64 v[146:147], s[24:25], 0, v[130:131]
	s_add_i32 m0, s8, 0x2000
	s_nop 0
	global_load_lds_dwordx4 v[146:147], off
	v_lshl_add_u64 v[146:147], v[218:219], 0, s[20:21]
	s_mov_b32 m0, s27
	s_nop 0
	global_load_lds_dwordx4 v[146:147], off
	v_lshl_add_u64 v[146:147], v[220:221], 0, s[20:21]
	s_mov_b32 m0, s31
	s_nop 0
	global_load_lds_dwordx4 v[146:147], off
	s_waitcnt vmcnt(8)
	s_waitcnt lgkmcnt(0)
	s_barrier
; #define PG8_STAGE(bufoff, gbase, voff) do { _Pragma("unroll") for (int _i = 0; _i < 2; ++_i) \
;         __builtin_amdgcn_global_load_lds((const unsigned*)((const char*)(gbase) + (voff)[_i]), (PG8_LAS unsigned*)(lds + (bufoff) + ldsw + _i * 8192), 16, 0, 0); } while (0)
; #define PG8_LDA(dst, b, h) do { _Pragma("unroll") for (int m = 0; m < 4; ++m) _Pragma("unroll") for (int k = 0; k < 2; ++k) dst[m][k] = *(const PG8_LAS bf16x8*)(lds + PG8_SA(b, h) + aoff + m * 2048 + k * 1024); } while (0)
; #define PG8_LDB(dst, b, h) do { _Pragma("unroll") for (int n = 0; n < 2; ++n) _Pragma("unroll") for (int k = 0; k < 2; ++k) dst[n][k] = *(const PG8_LAS bf16x8*)(lds + PG8_SB(b, h) + boff + n * 2048 + k * 1024); } while (0)
; #define PG8_MMA(ai, bj, At, Bt) do { __builtin_amdgcn_s_setprio(1); _Pragma("unroll") for (int m = 0; m < 4; ++m) _Pragma("unroll") for (int n = 0; n < 2; ++n) _Pragma("unroll") for (int k = 0; k < 2; ++k) \
;         acc[ai][bj][m][n] = __builtin_amdgcn_mfma_f32_16x16x32_bf16(Bt[n][k], At[m][k], acc[ai][bj][m][n], 0, 0, 0); __builtin_amdgcn_s_setprio(0); } while (0)
; template <class Epi, class Sched, bool ALIGN_EPI = false, bool SP2 = false>
; __device__ __forceinline__ void gemm_phase(PG8_LAS unsigned char* lds, const Gemm g, const Sched& S, const Epi& E, const int wid) {
;     ...
;         for (int t = 0; t < nt; t += 2) {
;             const bool last = (t == nt - 2);
;             const char* a1 = cA + (size_t)(t + 1) * kstep;
;             const char* a2 = last ? nA : cA + (size_t)(t + 2) * kstep; const char* b2 = last ? nB : cB + (size_t)(t + 2) * kstep;
;             const char* a3 = a2 + kstep; const char* b3 = b2 + kstep;
;             if (last && has_next) S.a_ready(nxt);
;             if constexpr (SP2) {
;             PG8_LDB(B0, 0, 0); PG8_LDB(B1, 0, 1); PG8_SCHED; PG8_LDA(At, 0, 0); PG8_STAGE(PG8_SA(1, 1), a1 + hsA, voffA);
;             PG8_WAIT_V(8); PG8_WAIT_L(0); PG8_BAR; PG8_MMA(0, 0, At, B0); PG8_MMA(0, 1, At, B1); PG8_BAR; PG8_SCHED;
;             PG8_LDA(At, 0, 1); PG8_STAGE(PG8_SB(0, 0), b2, voffB); PG8_STAGE(PG8_SB(0, 1), b2 + hsB, voffB); PG8_STAGE(PG8_SA(0, 0), a2, voffA);
;             PG8_WAIT_V(8); PG8_WAIT_L(0); PG8_BAR; PG8_MMA(1, 0, At, B0); PG8_MMA(1, 1, At, B1); PG8_BAR; PG8_SCHED;
;     ...
;             PG8_WAIT_V(8); PG8_WAIT_L(0); PG8_BAR; PG8_MMA(1, 0, At, B0); PG8_MMA(1, 1, At, B1); PG8_BAR; PG8_SCHED;
	s_waitcnt lgkmcnt(0)
	v_mfma_f32_16x16x32_bf16 v[62:65], v[152:155], v[184:187], v[62:65]
	v_mfma_f32_16x16x32_bf16 v[58:61], v[160:163], v[184:187], v[58:61]
	v_mfma_f32_16x16x32_bf16 v[46:49], v[152:155], v[192:195], v[46:49]
	v_mfma_f32_16x16x32_bf16 v[42:45], v[160:163], v[192:195], v[42:45]
	v_mfma_f32_16x16x32_bf16 v[30:33], v[152:155], v[200:203], v[30:33]
	v_mfma_f32_16x16x32_bf16 v[26:29], v[160:163], v[200:203], v[26:29]
	v_mfma_f32_16x16x32_bf16 v[14:17], v[152:155], v[208:211], v[14:17]
	v_mfma_f32_16x16x32_bf16 v[10:13], v[160:163], v[208:211], v[10:13]
	v_mfma_f32_16x16x32_bf16 v[62:65], v[156:159], v[188:191], v[62:65]
	v_mfma_f32_16x16x32_bf16 v[58:61], v[164:167], v[188:191], v[58:61]
	v_mfma_f32_16x16x32_bf16 v[46:49], v[156:159], v[196:199], v[46:49]
	v_mfma_f32_16x16x32_bf16 v[42:45], v[164:167], v[196:199], v[42:45]
	v_mfma_f32_16x16x32_bf16 v[30:33], v[156:159], v[204:207], v[30:33]
	v_mfma_f32_16x16x32_bf16 v[26:29], v[164:167], v[204:207], v[26:29]
	v_mfma_f32_16x16x32_bf16 v[14:17], v[156:159], v[212:215], v[14:17]
	v_mfma_f32_16x16x32_bf16 v[10:13], v[164:167], v[212:215], v[10:13]
	v_mfma_f32_16x16x32_bf16 v[54:57], v[168:171], v[184:187], v[54:57]
	v_mfma_f32_16x16x32_bf16 v[50:53], v[176:179], v[184:187], v[50:53]
	v_mfma_f32_16x16x32_bf16 v[38:41], v[168:171], v[192:195], v[38:41]
	v_mfma_f32_16x16x32_bf16 v[34:37], v[176:179], v[192:195], v[34:37]
	v_mfma_f32_16x16x32_bf16 v[22:25], v[168:171], v[200:203], v[22:25]
	v_mfma_f32_16x16x32_bf16 v[18:21], v[176:179], v[200:203], v[18:21]
	v_mfma_f32_16x16x32_bf16 v[6:9], v[168:171], v[208:211], v[6:9]
	v_mfma_f32_16x16x32_bf16 v[2:5], v[176:179], v[208:211], v[2:5]
	v_mfma_f32_16x16x32_bf16 v[54:57], v[172:175], v[188:191], v[54:57]
	v_mfma_f32_16x16x32_bf16 v[50:53], v[180:183], v[188:191], v[50:53]
	v_mfma_f32_16x16x32_bf16 v[38:41], v[172:175], v[196:199], v[38:41]
	v_mfma_f32_16x16x32_bf16 v[34:37], v[180:183], v[196:199], v[34:37]
	v_mfma_f32_16x16x32_bf16 v[22:25], v[172:175], v[204:207], v[22:25]
	v_mfma_f32_16x16x32_bf16 v[18:21], v[180:183], v[204:207], v[18:21]
	v_mfma_f32_16x16x32_bf16 v[6:9], v[172:175], v[212:215], v[6:9]
	v_mfma_f32_16x16x32_bf16 v[2:5], v[180:183], v[212:215], v[2:5]
	s_barrier
	s_add_i32 s69, s69, 2
	s_add_u32 s56, s56, 0x100
	s_addc_u32 s57, s57, 0
	s_add_u32 s67, s67, 0x100
	s_addc_u32 s68, s68, 0
	s_cmp_gt_u32 s69, 13
	s_cbranch_scc0 .LBB0_1474
	s_branch .Lp9_exit
.LBB0_1474:
	ds_read_b128 v[152:155], v149
	ds_read_b128 v[156:159], v149 offset:1024
	ds_read_b128 v[160:163], v149 offset:2048
	ds_read_b128 v[164:167], v149 offset:3072
	ds_read_b128 v[168:171], v150
	ds_read_b128 v[172:175], v150 offset:1024
	ds_read_b128 v[176:179], v150 offset:2048
	ds_read_b128 v[180:183], v150 offset:3072
	s_add_u32 s8, s56, 0xfffc0080
	s_addc_u32 s9, s57, -1
	s_cmp_eq_u32 s69, 12
	s_cselect_b32 s61, s49, s9
	s_cselect_b32 s60, s65, s8
	s_cselect_b32 s59, s47, s68
	s_cselect_b32 s58, s66, s67
	v_lshl_add_u64 v[146:147], s[56:57], 0, v[138:139]
	s_add_i32 m0, s85, 0xc000
	ds_read_b128 v[184:187], v151
	ds_read_b128 v[188:191], v151 offset:1024
	ds_read_b128 v[192:195], v151 offset:2048
	ds_read_b128 v[196:199], v151 offset:3072
	ds_read_b128 v[200:203], v151 offset:4096
	ds_read_b128 v[204:207], v151 offset:5120
	ds_read_b128 v[208:211], v151 offset:6144
	ds_read_b128 v[212:215], v151 offset:7168
	global_load_lds_dwordx4 v[146:147], off
	v_lshl_add_u64 v[146:147], s[56:57], 0, v[140:141]
	s_add_i32 m0, s85, 0xe000
	s_nop 0
	global_load_lds_dwordx4 v[146:147], off
	s_waitcnt vmcnt(8)
	s_waitcnt lgkmcnt(0)
	s_barrier
	s_waitcnt lgkmcnt(0)
	v_mfma_f32_16x16x32_bf16 v[126:129], v[152:155], v[184:187], v[126:129]
	v_mfma_f32_16x16x32_bf16 v[122:125], v[160:163], v[184:187], v[122:125]
	v_mfma_f32_16x16x32_bf16 v[110:113], v[152:155], v[192:195], v[110:113]
	v_mfma_f32_16x16x32_bf16 v[106:109], v[160:163], v[192:195], v[106:109]
	v_mfma_f32_16x16x32_bf16 v[94:97], v[152:155], v[200:203], v[94:97]
	v_mfma_f32_16x16x32_bf16 v[90:93], v[160:163], v[200:203], v[90:93]
	v_mfma_f32_16x16x32_bf16 v[78:81], v[152:155], v[208:211], v[78:81]
	v_mfma_f32_16x16x32_bf16 v[74:77], v[160:163], v[208:211], v[74:77]
	v_mfma_f32_16x16x32_bf16 v[126:129], v[156:159], v[188:191], v[126:129]
	v_mfma_f32_16x16x32_bf16 v[122:125], v[164:167], v[188:191], v[122:125]
	v_mfma_f32_16x16x32_bf16 v[110:113], v[156:159], v[196:199], v[110:113]
	v_mfma_f32_16x16x32_bf16 v[106:109], v[164:167], v[196:199], v[106:109]
	v_mfma_f32_16x16x32_bf16 v[94:97], v[156:159], v[204:207], v[94:97]
	v_mfma_f32_16x16x32_bf16 v[90:93], v[164:167], v[204:207], v[90:93]
	v_mfma_f32_16x16x32_bf16 v[78:81], v[156:159], v[212:215], v[78:81]
	v_mfma_f32_16x16x32_bf16 v[74:77], v[164:167], v[212:215], v[74:77]
	v_mfma_f32_16x16x32_bf16 v[118:121], v[168:171], v[184:187], v[118:121]
	v_mfma_f32_16x16x32_bf16 v[114:117], v[176:179], v[184:187], v[114:117]
	v_mfma_f32_16x16x32_bf16 v[102:105], v[168:171], v[192:195], v[102:105]
	v_mfma_f32_16x16x32_bf16 v[98:101], v[176:179], v[192:195], v[98:101]
	v_mfma_f32_16x16x32_bf16 v[86:89], v[168:171], v[200:203], v[86:89]
	v_mfma_f32_16x16x32_bf16 v[82:85], v[176:179], v[200:203], v[82:85]
	v_mfma_f32_16x16x32_bf16 v[70:73], v[168:171], v[208:211], v[70:73]
	v_mfma_f32_16x16x32_bf16 v[66:69], v[176:179], v[208:211], v[66:69]
	v_mfma_f32_16x16x32_bf16 v[118:121], v[172:175], v[188:191], v[118:121]
	v_mfma_f32_16x16x32_bf16 v[114:117], v[180:183], v[188:191], v[114:117]
	v_mfma_f32_16x16x32_bf16 v[102:105], v[172:175], v[196:199], v[102:105]
	v_mfma_f32_16x16x32_bf16 v[98:101], v[180:183], v[196:199], v[98:101]
	v_mfma_f32_16x16x32_bf16 v[86:89], v[172:175], v[204:207], v[86:89]
	v_mfma_f32_16x16x32_bf16 v[82:85], v[180:183], v[204:207], v[82:85]
	v_mfma_f32_16x16x32_bf16 v[70:73], v[172:175], v[212:215], v[70:73]
	v_mfma_f32_16x16x32_bf16 v[66:69], v[180:183], v[212:215], v[66:69]
	s_barrier
; #define PG8_STAGE(bufoff, gbase, voff) do { _Pragma("unroll") for (int _i = 0; _i < 2; ++_i) \
;         __builtin_amdgcn_global_load_lds((const unsigned*)((const char*)(gbase) + (voff)[_i]), (PG8_LAS unsigned*)(lds + (bufoff) + ldsw + _i * 8192), 16, 0, 0); } while (0)
; #define PG8_LDA(dst, b, h) do { _Pragma("unroll") for (int m = 0; m < 4; ++m) _Pragma("unroll") for (int k = 0; k < 2; ++k) dst[m][k] = *(const PG8_LAS bf16x8*)(lds + PG8_SA(b, h) + aoff + m * 2048 + k * 1024); } while (0)
; #define PG8_LDB(dst, b, h) do { _Pragma("unroll") for (int n = 0; n < 2; ++n) _Pragma("unroll") for (int k = 0; k < 2; ++k) dst[n][k] = *(const PG8_LAS bf16x8*)(lds + PG8_SB(b, h) + boff + n * 2048 + k * 1024); } while (0)
; #define PG8_MMA(ai, bj, At, Bt) do { __builtin_amdgcn_s_setprio(1); _Pragma("unroll") for (int m = 0; m < 4; ++m) _Pragma("unroll") for (int n = 0; n < 2; ++n) _Pragma("unroll") for (int k = 0; k < 2; ++k) \
;         acc[ai][bj][m][n] = __builtin_amdgcn_mfma_f32_16x16x32_bf16(Bt[n][k], At[m][k], acc[ai][bj][m][n], 0, 0, 0); __builtin_amdgcn_s_setprio(0); } while (0)
; #define PG8_WAIT_V(n) asm volatile("s_waitcnt vmcnt(" #n ")" ::: "memory")
; #define PG8_WAIT_L(n) asm volatile("s_waitcnt lgkmcnt(" #n ")" ::: "memory")
; #define PG8_BAR __builtin_amdgcn_s_barrier()
; #define PG8_SCHED __builtin_amdgcn_sched_barrier(0)
; template <class Epi, class Sched, bool ALIGN_EPI = false, bool SP2 = false>
; __device__ __forceinline__ void gemm_phase(PG8_LAS unsigned char* lds, const Gemm g, const Sched& S, const Epi& E, const int wid) {
;     ...
;             PG8_LDA(At, 0, 1); PG8_STAGE(PG8_SB(0, 0), b2, voffB); PG8_STAGE(PG8_SB(0, 1), b2 + hsB, voffB); PG8_STAGE(PG8_SA(0, 0), a2, voffA);
;             PG8_WAIT_V(8); PG8_WAIT_L(0); PG8_BAR; PG8_MMA(1, 0, At, B0); PG8_MMA(1, 1, At, B1); PG8_BAR; PG8_SCHED;
;             PG8_LDB(B0, 1, 0); PG8_LDB(B1, 1, 1); PG8_SCHED; PG8_LDA(At, 1, 0); PG8_STAGE(PG8_SA(0, 1), a2 + hsA, voffA);
;             PG8_WAIT_V(8); PG8_WAIT_L(0); PG8_BAR; PG8_MMA(0, 0, At, B0); PG8_MMA(0, 1, At, B1); PG8_BAR; PG8_SCHED;
	s_add_i32 s8, s35, s28
	v_lshl_add_u64 v[146:147], s[58:59], 0, v[134:135]
	s_mov_b32 m0, s8
	ds_read_b128 v[184:187], v151 offset:16384
	ds_read_b128 v[188:191], v151 offset:17408
	ds_read_b128 v[192:195], v151 offset:18432
	ds_read_b128 v[196:199], v151 offset:19456
	ds_read_b128 v[200:203], v151 offset:20480
	ds_read_b128 v[204:207], v151 offset:21504
	ds_read_b128 v[208:211], v151 offset:22528
	ds_read_b128 v[212:215], v151 offset:23552
	global_load_lds_dwordx4 v[146:147], off
	s_add_i32 m0, s8, 0x2000
	s_add_u32 s24, s58, 0x40000
	v_lshl_add_u64 v[216:217], s[58:59], 0, v[130:131]
	s_addc_u32 s25, s59, 0
	s_add_i32 s8, s36, s28
	global_load_lds_dwordx4 v[216:217], off
	v_lshl_add_u64 v[218:219], s[24:25], 0, v[134:135]
	s_mov_b32 m0, s8
	v_lshl_add_u64 v[220:221], s[60:61], 0, v[132:133]
	global_load_lds_dwordx4 v[218:219], off
	v_lshl_add_u64 v[218:219], s[24:25], 0, v[130:131]
	s_add_i32 m0, s8, 0x2000
	s_nop 0
	global_load_lds_dwordx4 v[218:219], off
	v_lshl_add_u64 v[218:219], s[60:61], 0, v[136:137]
	s_mov_b32 m0, s85
	s_nop 0
	global_load_lds_dwordx4 v[218:219], off
	s_mov_b32 m0, s17
	s_nop 0
	global_load_lds_dwordx4 v[220:221], off
	s_waitcnt vmcnt(8)
	s_waitcnt lgkmcnt(0)
	s_barrier
	s_waitcnt lgkmcnt(0)
	v_mfma_f32_16x16x32_bf16 v[62:65], v[152:155], v[184:187], v[62:65]
	v_mfma_f32_16x16x32_bf16 v[58:61], v[160:163], v[184:187], v[58:61]
	v_mfma_f32_16x16x32_bf16 v[46:49], v[152:155], v[192:195], v[46:49]
	v_mfma_f32_16x16x32_bf16 v[42:45], v[160:163], v[192:195], v[42:45]
	v_mfma_f32_16x16x32_bf16 v[30:33], v[152:155], v[200:203], v[30:33]
	v_mfma_f32_16x16x32_bf16 v[26:29], v[160:163], v[200:203], v[26:29]
	v_mfma_f32_16x16x32_bf16 v[14:17], v[152:155], v[208:211], v[14:17]
	v_mfma_f32_16x16x32_bf16 v[10:13], v[160:163], v[208:211], v[10:13]
	v_mfma_f32_16x16x32_bf16 v[62:65], v[156:159], v[188:191], v[62:65]
	v_mfma_f32_16x16x32_bf16 v[58:61], v[164:167], v[188:191], v[58:61]
	v_mfma_f32_16x16x32_bf16 v[46:49], v[156:159], v[196:199], v[46:49]
	v_mfma_f32_16x16x32_bf16 v[42:45], v[164:167], v[196:199], v[42:45]
	v_mfma_f32_16x16x32_bf16 v[30:33], v[156:159], v[204:207], v[30:33]
	v_mfma_f32_16x16x32_bf16 v[26:29], v[164:167], v[204:207], v[26:29]
	v_mfma_f32_16x16x32_bf16 v[14:17], v[156:159], v[212:215], v[14:17]
	v_mfma_f32_16x16x32_bf16 v[10:13], v[164:167], v[212:215], v[10:13]
	v_mfma_f32_16x16x32_bf16 v[54:57], v[168:171], v[184:187], v[54:57]
	v_mfma_f32_16x16x32_bf16 v[50:53], v[176:179], v[184:187], v[50:53]
	v_mfma_f32_16x16x32_bf16 v[38:41], v[168:171], v[192:195], v[38:41]
	v_mfma_f32_16x16x32_bf16 v[34:37], v[176:179], v[192:195], v[34:37]
	v_mfma_f32_16x16x32_bf16 v[22:25], v[168:171], v[200:203], v[22:25]
	v_mfma_f32_16x16x32_bf16 v[18:21], v[176:179], v[200:203], v[18:21]
	v_mfma_f32_16x16x32_bf16 v[6:9], v[168:171], v[208:211], v[6:9]
	v_mfma_f32_16x16x32_bf16 v[2:5], v[176:179], v[208:211], v[2:5]
	v_mfma_f32_16x16x32_bf16 v[54:57], v[172:175], v[188:191], v[54:57]
	v_mfma_f32_16x16x32_bf16 v[50:53], v[180:183], v[188:191], v[50:53]
	v_mfma_f32_16x16x32_bf16 v[38:41], v[172:175], v[196:199], v[38:41]
	v_mfma_f32_16x16x32_bf16 v[34:37], v[180:183], v[196:199], v[34:37]
	v_mfma_f32_16x16x32_bf16 v[22:25], v[172:175], v[204:207], v[22:25]
	v_mfma_f32_16x16x32_bf16 v[18:21], v[180:183], v[204:207], v[18:21]
	v_mfma_f32_16x16x32_bf16 v[6:9], v[172:175], v[212:215], v[6:9]
	v_mfma_f32_16x16x32_bf16 v[2:5], v[180:183], v[212:215], v[2:5]
	s_barrier
	s_add_i32 s8, 0, 0x18000
	s_add_i32 s9, 0, 0x1c000
	v_add_u32_e32 v164, s8, v148
	v_add_u32_e32 v180, s9, v148
	ds_read_b128 v[152:155], v164
	ds_read_b128 v[156:159], v164 offset:1024
	ds_read_b128 v[160:163], v164 offset:2048
	ds_read_b128 v[164:167], v164 offset:3072
	ds_read_b128 v[168:171], v180
	ds_read_b128 v[172:175], v180 offset:1024
	ds_read_b128 v[176:179], v180 offset:2048
	ds_read_b128 v[180:183], v180 offset:3072
	s_add_u32 s24, s60, 0x40000
	s_addc_u32 s25, s61, 0
	s_mov_b32 m0, s18
	v_lshl_add_u64 v[222:223], s[24:25], 0, v[136:137]
	ds_read_b128 v[184:187], v151 offset:32768
	ds_read_b128 v[188:191], v151 offset:33792
	ds_read_b128 v[192:195], v151 offset:34816
	ds_read_b128 v[196:199], v151 offset:35840
	ds_read_b128 v[200:203], v151 offset:36864
	ds_read_b128 v[204:207], v151 offset:37888
	ds_read_b128 v[208:211], v151 offset:38912
	ds_read_b128 v[212:215], v151 offset:39936
	global_load_lds_dwordx4 v[222:223], off
	v_lshl_add_u64 v[222:223], s[24:25], 0, v[132:133]
	s_mov_b32 m0, s19
	s_nop 0
	global_load_lds_dwordx4 v[222:223], off
	s_waitcnt vmcnt(8)
	s_waitcnt lgkmcnt(0)
	s_barrier
; #define PG8_STAGE(bufoff, gbase, voff) do { _Pragma("unroll") for (int _i = 0; _i < 2; ++_i) \
;         __builtin_amdgcn_global_load_lds((const unsigned*)((const char*)(gbase) + (voff)[_i]), (PG8_LAS unsigned*)(lds + (bufoff) + ldsw + _i * 8192), 16, 0, 0); } while (0)
; #define PG8_LDA(dst, b, h) do { _Pragma("unroll") for (int m = 0; m < 4; ++m) _Pragma("unroll") for (int k = 0; k < 2; ++k) dst[m][k] = *(const PG8_LAS bf16x8*)(lds + PG8_SA(b, h) + aoff + m * 2048 + k * 1024); } while (0)
; #define PG8_MMA(ai, bj, At, Bt) do { __builtin_amdgcn_s_setprio(1); _Pragma("unroll") for (int m = 0; m < 4; ++m) _Pragma("unroll") for (int n = 0; n < 2; ++n) _Pragma("unroll") for (int k = 0; k < 2; ++k) \
;         acc[ai][bj][m][n] = __builtin_amdgcn_mfma_f32_16x16x32_bf16(Bt[n][k], At[m][k], acc[ai][bj][m][n], 0, 0, 0); __builtin_amdgcn_s_setprio(0); } while (0)
; #define PG8_WAIT_V(n) asm volatile("s_waitcnt vmcnt(" #n ")" ::: "memory")
; #define PG8_WAIT_L(n) asm volatile("s_waitcnt lgkmcnt(" #n ")" ::: "memory")
; #define PG8_BAR __builtin_amdgcn_s_barrier()
; #define PG8_SCHED __builtin_amdgcn_sched_barrier(0)
; template <class Epi, class Sched, bool ALIGN_EPI = false, bool SP2 = false>
; __device__ __forceinline__ void gemm_phase(PG8_LAS unsigned char* lds, const Gemm g, const Sched& S, const Epi& E, const int wid) {
;     ...
;             PG8_WAIT_V(8); PG8_WAIT_L(0); PG8_BAR; PG8_MMA(0, 0, At, B0); PG8_MMA(0, 1, At, B1); PG8_BAR; PG8_SCHED;
;             PG8_LDA(At, 1, 1); PG8_STAGE(PG8_SB(1, 0), b3, voffB); PG8_STAGE(PG8_SB(1, 1), b3 + hsB, voffB); PG8_STAGE(PG8_SA(1, 0), a3, voffA);
;             PG8_WAIT_V(8); PG8_WAIT_L(0); PG8_BAR; PG8_MMA(1, 0, At, B0); PG8_MMA(1, 1, At, B1); PG8_BAR; PG8_SCHED;
;     ...
;         if constexpr (ALIGN_EPI) { if (wr == 0) PG8_BAR; }
	s_waitcnt lgkmcnt(0)
	v_mfma_f32_16x16x32_bf16 v[126:129], v[152:155], v[184:187], v[126:129]
	v_mfma_f32_16x16x32_bf16 v[122:125], v[160:163], v[184:187], v[122:125]
	v_mfma_f32_16x16x32_bf16 v[110:113], v[152:155], v[192:195], v[110:113]
	v_mfma_f32_16x16x32_bf16 v[106:109], v[160:163], v[192:195], v[106:109]
	v_mfma_f32_16x16x32_bf16 v[94:97], v[152:155], v[200:203], v[94:97]
	v_mfma_f32_16x16x32_bf16 v[90:93], v[160:163], v[200:203], v[90:93]
	v_mfma_f32_16x16x32_bf16 v[78:81], v[152:155], v[208:211], v[78:81]
	v_mfma_f32_16x16x32_bf16 v[74:77], v[160:163], v[208:211], v[74:77]
	v_mfma_f32_16x16x32_bf16 v[126:129], v[156:159], v[188:191], v[126:129]
	v_mfma_f32_16x16x32_bf16 v[122:125], v[164:167], v[188:191], v[122:125]
	v_mfma_f32_16x16x32_bf16 v[110:113], v[156:159], v[196:199], v[110:113]
	v_mfma_f32_16x16x32_bf16 v[106:109], v[164:167], v[196:199], v[106:109]
	v_mfma_f32_16x16x32_bf16 v[94:97], v[156:159], v[204:207], v[94:97]
	v_mfma_f32_16x16x32_bf16 v[90:93], v[164:167], v[204:207], v[90:93]
	v_mfma_f32_16x16x32_bf16 v[78:81], v[156:159], v[212:215], v[78:81]
	v_mfma_f32_16x16x32_bf16 v[74:77], v[164:167], v[212:215], v[74:77]
	v_mfma_f32_16x16x32_bf16 v[118:121], v[168:171], v[184:187], v[118:121]
	v_mfma_f32_16x16x32_bf16 v[114:117], v[176:179], v[184:187], v[114:117]
	v_mfma_f32_16x16x32_bf16 v[102:105], v[168:171], v[192:195], v[102:105]
	v_mfma_f32_16x16x32_bf16 v[98:101], v[176:179], v[192:195], v[98:101]
	v_mfma_f32_16x16x32_bf16 v[86:89], v[168:171], v[200:203], v[86:89]
	v_mfma_f32_16x16x32_bf16 v[82:85], v[176:179], v[200:203], v[82:85]
	v_mfma_f32_16x16x32_bf16 v[70:73], v[168:171], v[208:211], v[70:73]
	v_mfma_f32_16x16x32_bf16 v[66:69], v[176:179], v[208:211], v[66:69]
	v_mfma_f32_16x16x32_bf16 v[118:121], v[172:175], v[188:191], v[118:121]
	v_mfma_f32_16x16x32_bf16 v[114:117], v[180:183], v[188:191], v[114:117]
	v_mfma_f32_16x16x32_bf16 v[102:105], v[172:175], v[196:199], v[102:105]
	v_mfma_f32_16x16x32_bf16 v[98:101], v[180:183], v[196:199], v[98:101]
	v_mfma_f32_16x16x32_bf16 v[86:89], v[172:175], v[204:207], v[86:89]
	v_mfma_f32_16x16x32_bf16 v[82:85], v[180:183], v[204:207], v[82:85]
	v_mfma_f32_16x16x32_bf16 v[70:73], v[172:175], v[212:215], v[70:73]
	v_mfma_f32_16x16x32_bf16 v[66:69], v[180:183], v[212:215], v[66:69]
	s_barrier
	s_add_i32 s8, s8, s28
	v_lshl_add_u64 v[146:147], v[146:147], 0, s[20:21]
	s_mov_b32 m0, s8
	ds_read_b128 v[184:187], v151 offset:49152
	ds_read_b128 v[188:191], v151 offset:50176
	ds_read_b128 v[192:195], v151 offset:51200
	ds_read_b128 v[196:199], v151 offset:52224
	ds_read_b128 v[200:203], v151 offset:53248
	ds_read_b128 v[204:207], v151 offset:54272
	ds_read_b128 v[208:211], v151 offset:55296
	ds_read_b128 v[212:215], v151 offset:56320
	global_load_lds_dwordx4 v[146:147], off
	s_add_i32 m0, s8, 0x2000
	s_add_u32 s24, s58, 0x40080
	v_lshl_add_u64 v[146:147], v[216:217], 0, s[20:21]
	s_addc_u32 s25, s59, 0
	s_add_i32 s8, s9, s28
	global_load_lds_dwordx4 v[146:147], off
	v_lshl_add_u64 v[146:147], s[24:25], 0, v[134:135]
	s_mov_b32 m0, s8
	s_nop 0
	global_load_lds_dwordx4 v[146:147], off
	v_lshl_add_u64 v[146:147], s[24:25], 0, v[130:131]
	s_add_i32 m0, s8, 0x2000
	s_nop 0
	global_load_lds_dwordx4 v[146:147], off
	v_lshl_add_u64 v[146:147], v[218:219], 0, s[20:21]
	s_mov_b32 m0, s27
	s_nop 0
	global_load_lds_dwordx4 v[146:147], off
	v_lshl_add_u64 v[146:147], v[220:221], 0, s[20:21]
	s_mov_b32 m0, s31
	s_nop 0
	global_load_lds_dwordx4 v[146:147], off
	s_waitcnt vmcnt(8)
	s_waitcnt lgkmcnt(0)
	s_barrier
	s_waitcnt lgkmcnt(0)
	v_mfma_f32_16x16x32_bf16 v[62:65], v[152:155], v[184:187], v[62:65]
	v_mfma_f32_16x16x32_bf16 v[58:61], v[160:163], v[184:187], v[58:61]
	v_mfma_f32_16x16x32_bf16 v[46:49], v[152:155], v[192:195], v[46:49]
	v_mfma_f32_16x16x32_bf16 v[42:45], v[160:163], v[192:195], v[42:45]
	v_mfma_f32_16x16x32_bf16 v[30:33], v[152:155], v[200:203], v[30:33]
	v_mfma_f32_16x16x32_bf16 v[26:29], v[160:163], v[200:203], v[26:29]
	v_mfma_f32_16x16x32_bf16 v[14:17], v[152:155], v[208:211], v[14:17]
	v_mfma_f32_16x16x32_bf16 v[10:13], v[160:163], v[208:211], v[10:13]
	v_mfma_f32_16x16x32_bf16 v[62:65], v[156:159], v[188:191], v[62:65]
	v_mfma_f32_16x16x32_bf16 v[58:61], v[164:167], v[188:191], v[58:61]
	v_mfma_f32_16x16x32_bf16 v[46:49], v[156:159], v[196:199], v[46:49]
	v_mfma_f32_16x16x32_bf16 v[42:45], v[164:167], v[196:199], v[42:45]
	v_mfma_f32_16x16x32_bf16 v[30:33], v[156:159], v[204:207], v[30:33]
	v_mfma_f32_16x16x32_bf16 v[26:29], v[164:167], v[204:207], v[26:29]
	v_mfma_f32_16x16x32_bf16 v[14:17], v[156:159], v[212:215], v[14:17]
	v_mfma_f32_16x16x32_bf16 v[10:13], v[164:167], v[212:215], v[10:13]
	v_mfma_f32_16x16x32_bf16 v[54:57], v[168:171], v[184:187], v[54:57]
	v_mfma_f32_16x16x32_bf16 v[50:53], v[176:179], v[184:187], v[50:53]
	v_mfma_f32_16x16x32_bf16 v[38:41], v[168:171], v[192:195], v[38:41]
	v_mfma_f32_16x16x32_bf16 v[34:37], v[176:179], v[192:195], v[34:37]
	v_mfma_f32_16x16x32_bf16 v[22:25], v[168:171], v[200:203], v[22:25]
	v_mfma_f32_16x16x32_bf16 v[18:21], v[176:179], v[200:203], v[18:21]
	v_mfma_f32_16x16x32_bf16 v[6:9], v[168:171], v[208:211], v[6:9]
	v_mfma_f32_16x16x32_bf16 v[2:5], v[176:179], v[208:211], v[2:5]
	v_mfma_f32_16x16x32_bf16 v[54:57], v[172:175], v[188:191], v[54:57]
	v_mfma_f32_16x16x32_bf16 v[50:53], v[180:183], v[188:191], v[50:53]
	v_mfma_f32_16x16x32_bf16 v[38:41], v[172:175], v[196:199], v[38:41]
	v_mfma_f32_16x16x32_bf16 v[34:37], v[180:183], v[196:199], v[34:37]
	v_mfma_f32_16x16x32_bf16 v[22:25], v[172:175], v[204:207], v[22:25]
	v_mfma_f32_16x16x32_bf16 v[18:21], v[180:183], v[204:207], v[18:21]
	v_mfma_f32_16x16x32_bf16 v[6:9], v[172:175], v[212:215], v[6:9]
	v_mfma_f32_16x16x32_bf16 v[2:5], v[180:183], v[212:215], v[2:5]
	s_barrier
	s_add_i32 s69, s69, 2
	s_add_u32 s56, s56, 0x100
	s_addc_u32 s57, s57, 0
	s_add_u32 s67, s67, 0x100
	s_addc_u32 s68, s68, 0
	s_cmp_gt_u32 s69, 13
	s_cbranch_scc0 .LBB0_1474
	s_setprio 0

;     __device__ __forceinline__ const char* a_ptr(const Gemm& g, const Unit& u, size_t tsA) const { return (const char*)g.A + (size_t)u.pm * tsA + (size_t)u.pn * g.a_pn_bytes + (u.ks > 0 ? (size_t)u.ks * g.ks_bytes : 0); }
;     __device__ __forceinline__ const char* b_ptr(const Gemm& g, const Unit& u, size_t tsB) const { return (const char*)g.Bt + (size_t)u.pn * tsB + (u.ks > 0 ? (size_t)u.ks * g.ks_bytes : 0); }
;     __device__ __forceinline__ const char* a_ptr(const Gemm& g, const Unit& u, size_t tsA) const { return (const char*)g.A + (size_t)u.pm * tsA + (size_t)u.pn * g.a_pn_bytes + (u.ks > 0 ? (size_t)u.ks * g.ks_bytes : 0); }
;     __device__ __forceinline__ const char* b_ptr(const Gemm& g, const Unit& u, size_t tsB) const { return (const char*)g.Bt + (size_t)u.pn * tsB + (u.ks > 0 ? (size_t)u.ks * g.ks_bytes : 0); }
; #define PG8_LDA(dst, b, h) do { _Pragma("unroll") for (int m = 0; m < 4; ++m) _Pragma("unroll") for (int k = 0; k < 2; ++k) dst[m][k] = *(const PG8_LAS bf16x8*)(lds + PG8_SA(b, h) + aoff + m * 2048 + k * 1024); } while (0)
; template <class Epi, class Sched, bool ALIGN_EPI = false, bool SP2 = false>
; __device__ __forceinline__ void gemm_phase(PG8_LAS unsigned char* lds, const Gemm g, const Sched& S, const Epi& E, const int wid) {
;     ...
;         const bool has_next = S.next(ui + 1, nxt);
;         const char* nA = has_next ? S.a_ptr(g, nxt, tsA) : cA; const char* nB = has_next ? S.b_ptr(g, nxt, tsB) : cB;
;         const int nt = cur.ks >= 0 ? g.nt_split : ntfull;
; #pragma unroll 1
;         for (int t = 0; t < nt; t += 2) {
;             const bool last = (t == nt - 2);
;             const char* a1 = cA + (size_t)(t + 1) * kstep;
;             const char* a2 = last ? nA : cA + (size_t)(t + 2) * kstep; const char* b2 = last ? nB : cB + (size_t)(t + 2) * kstep;
;             const char* a3 = a2 + kstep; const char* b3 = b2 + kstep;
;             if (last && has_next) S.a_ready(nxt);
;             if constexpr (SP2) {
;             PG8_LDB(B0, 0, 0); PG8_LDB(B1, 0, 1); PG8_SCHED; PG8_LDA(At, 0, 0); PG8_STAGE(PG8_SA(1, 1), a1 + hsA, voffA);
;     ...
; #pragma unroll
;         for (int a = 0; a < 2; ++a)
; #pragma unroll
;             for (int b = 0; b < 2; ++b)
; #pragma unroll
;                 for (int m = 0; m < 4; ++m)
; #pragma unroll
;                     for (int n = 0; n < 2; ++n) acc[a][b][m][n] = (f32x4){0.f, 0.f, 0.f, 0.f};
.LBB0_1598:
	s_lshl_b64 s[24:25], s[16:17], 10
	s_cmp_gt_i32 s16, 0
	s_cselect_b32 s8, s25, 0
	s_cselect_b32 s9, s24, 0
	s_ashr_i32 s61, s60, 31
	s_lshl_b64 s[24:25], s[60:61], 21
	s_add_u32 s15, s31, s24
	s_addc_u32 s24, s35, s25
	s_add_u32 s64, s15, s9
	s_addc_u32 s65, s24, s8
	s_and_b64 s[24:25], s[58:59], exec
	s_cselect_b32 s15, s65, s13
	s_cselect_b32 s41, s64, s12
	s_ashr_i32 s63, s62, 31
	s_lshl_b64 s[24:25], s[62:63], 21
	s_add_u32 s24, s76, s24
	s_addc_u32 s25, s77, s25
	s_add_u32 s66, s24, s9
	s_addc_u32 s67, s25, s8
	s_and_b64 s[24:25], s[58:59], exec
	s_cselect_b32 s61, s67, s71
	s_cselect_b32 s63, s66, s70
	s_cmp_lt_i32 s40, 0
	s_cselect_b32 s69, 64, 8
	s_add_i32 s74, s69, -2
	s_add_u32 s12, s12, 0x100080
	s_addc_u32 s13, s13, 0
	s_add_u32 s75, s70, 0x100
	v_mov_b32_e32 v2, 0
	s_mov_b32 s72, 0
	s_addc_u32 vcc_lo, s71, 0
	v_mov_b32_e32 v3, v2
	v_mov_b32_e32 v4, v2
	v_mov_b32_e32 v5, v2
	v_mov_b32_e32 v6, v2
	v_mov_b32_e32 v7, v2
	v_mov_b32_e32 v8, v2
	v_mov_b32_e32 v9, v2
	v_mov_b32_e32 v10, v2
	v_mov_b32_e32 v11, v2
	v_mov_b32_e32 v12, v2
	v_mov_b32_e32 v13, v2
	v_mov_b32_e32 v14, v2
	v_mov_b32_e32 v15, v2
	v_mov_b32_e32 v16, v2
	v_mov_b32_e32 v17, v2
	v_mov_b32_e32 v22, v2
	v_mov_b32_e32 v23, v2
	v_mov_b32_e32 v24, v2
	v_mov_b32_e32 v25, v2
	v_mov_b32_e32 v30, v2
	v_mov_b32_e32 v31, v2
	v_mov_b32_e32 v32, v2
	v_mov_b32_e32 v33, v2
	v_mov_b32_e32 v38, v2
	v_mov_b32_e32 v39, v2
	v_mov_b32_e32 v40, v2
	v_mov_b32_e32 v41, v2
	v_mov_b32_e32 v46, v2
	v_mov_b32_e32 v47, v2
	v_mov_b32_e32 v48, v2
	v_mov_b32_e32 v49, v2
	v_mov_b32_e32 v18, v2
	v_mov_b32_e32 v19, v2
	v_mov_b32_e32 v20, v2
	v_mov_b32_e32 v21, v2
	v_mov_b32_e32 v26, v2
	v_mov_b32_e32 v27, v2
	v_mov_b32_e32 v28, v2
	v_mov_b32_e32 v29, v2
	v_mov_b32_e32 v34, v2
	v_mov_b32_e32 v35, v2
	v_mov_b32_e32 v36, v2
	v_mov_b32_e32 v37, v2
	v_mov_b32_e32 v42, v2
	v_mov_b32_e32 v43, v2
	v_mov_b32_e32 v44, v2
	v_mov_b32_e32 v45, v2
	v_mov_b32_e32 v50, v2
	v_mov_b32_e32 v51, v2
	v_mov_b32_e32 v52, v2
	v_mov_b32_e32 v53, v2
	v_mov_b32_e32 v54, v2
	v_mov_b32_e32 v55, v2
	v_mov_b32_e32 v56, v2
	v_mov_b32_e32 v57, v2
	v_mov_b32_e32 v58, v2
	v_mov_b32_e32 v59, v2
	v_mov_b32_e32 v60, v2
	v_mov_b32_e32 v61, v2
	v_mov_b32_e32 v62, v2
	v_mov_b32_e32 v63, v2
	v_mov_b32_e32 v64, v2
	v_mov_b32_e32 v65, v2
	v_mov_b32_e32 v66, v2
	v_mov_b32_e32 v67, v2
	v_mov_b32_e32 v68, v2
	v_mov_b32_e32 v69, v2
	v_mov_b32_e32 v70, v2
	v_mov_b32_e32 v71, v2
	v_mov_b32_e32 v72, v2
	v_mov_b32_e32 v73, v2
	v_mov_b32_e32 v74, v2
	v_mov_b32_e32 v75, v2
	v_mov_b32_e32 v76, v2
	v_mov_b32_e32 v77, v2
	v_mov_b32_e32 v78, v2
	v_mov_b32_e32 v79, v2
	v_mov_b32_e32 v80, v2
	v_mov_b32_e32 v81, v2
	v_mov_b32_e32 v86, v2
	v_mov_b32_e32 v87, v2
	v_mov_b32_e32 v88, v2
	v_mov_b32_e32 v89, v2
	v_mov_b32_e32 v94, v2
	v_mov_b32_e32 v95, v2
	v_mov_b32_e32 v96, v2
	v_mov_b32_e32 v97, v2
	v_mov_b32_e32 v102, v2
	v_mov_b32_e32 v103, v2
	v_mov_b32_e32 v104, v2
	v_mov_b32_e32 v105, v2
	v_mov_b32_e32 v110, v2
	v_mov_b32_e32 v111, v2
	v_mov_b32_e32 v112, v2
	v_mov_b32_e32 v113, v2
	v_mov_b32_e32 v82, v2
	v_mov_b32_e32 v83, v2
	v_mov_b32_e32 v84, v2
	v_mov_b32_e32 v85, v2
	v_mov_b32_e32 v90, v2
	v_mov_b32_e32 v91, v2
	v_mov_b32_e32 v92, v2
	v_mov_b32_e32 v93, v2
	v_mov_b32_e32 v98, v2
	v_mov_b32_e32 v99, v2
	v_mov_b32_e32 v100, v2
	v_mov_b32_e32 v101, v2
	v_mov_b32_e32 v106, v2
	v_mov_b32_e32 v107, v2
	v_mov_b32_e32 v108, v2
	v_mov_b32_e32 v109, v2
	v_mov_b32_e32 v114, v2
	v_mov_b32_e32 v115, v2
	v_mov_b32_e32 v116, v2
	v_mov_b32_e32 v117, v2
	v_mov_b32_e32 v118, v2
	v_mov_b32_e32 v119, v2
	v_mov_b32_e32 v120, v2
	v_mov_b32_e32 v121, v2
	v_mov_b32_e32 v122, v2
	v_mov_b32_e32 v123, v2
	v_mov_b32_e32 v124, v2
	v_mov_b32_e32 v125, v2
	v_mov_b32_e32 v126, v2
	v_mov_b32_e32 v127, v2
	v_mov_b32_e32 v128, v2
	v_mov_b32_e32 v129, v2
	s_cmp_lg_u64 s[6:7], 0
	s_cbranch_scc1 .Lsprio3
	s_setprio 1
.Lsprio3:
.LBB0_1599:
	ds_read_b128 v[130:133], v185
	ds_read_b128 v[134:137], v185 offset:1024
	ds_read_b128 v[138:141], v185 offset:2048
	ds_read_b128 v[142:145], v185 offset:3072
	ds_read_b128 v[146:149], v186
	ds_read_b128 v[150:153], v186 offset:1024
	ds_read_b128 v[154:157], v186 offset:2048
	ds_read_b128 v[158:161], v186 offset:3072
	s_add_i32 vcc_hi, s72, 2
	s_add_u32 s8, s12, 0xfff00080
	s_addc_u32 s9, s13, -1
	s_cmp_eq_u32 s74, s72
	s_cselect_b32 s72, s41, s8
	s_cselect_b32 s73, s15, s9
	s_cselect_b32 s71, s61, vcc_lo
	s_cselect_b32 s70, s63, s75
	v_lshl_add_u64 v[182:183], s[12:13], 0, v[166:167]
	s_add_i32 m0, s85, 0xc000
	ds_read_b128 v[174:177], v187
	ds_read_b128 v[178:181], v187 offset:1024
	ds_read_b128 v[190:193], v187 offset:2048
	ds_read_b128 v[194:197], v187 offset:3072
	ds_read_b128 v[198:201], v187 offset:4096
	ds_read_b128 v[202:205], v187 offset:5120
	ds_read_b128 v[206:209], v187 offset:6144
	ds_read_b128 v[210:213], v187 offset:7168
	global_load_lds_dwordx4 v[182:183], off
	v_lshl_add_u64 v[182:183], s[12:13], 0, v[168:169]
	s_add_i32 m0, s85, 0xe000
	s_nop 0
	global_load_lds_dwordx4 v[182:183], off
	s_waitcnt vmcnt(8)
	s_waitcnt lgkmcnt(0)
	s_barrier
; #define PG8_STAGE(bufoff, gbase, voff) do { _Pragma("unroll") for (int _i = 0; _i < 2; ++_i) \
;         __builtin_amdgcn_global_load_lds((const unsigned*)((const char*)(gbase) + (voff)[_i]), (PG8_LAS unsigned*)(lds + (bufoff) + ldsw + _i * 8192), 16, 0, 0); } while (0)
; #define PG8_LDA(dst, b, h) do { _Pragma("unroll") for (int m = 0; m < 4; ++m) _Pragma("unroll") for (int k = 0; k < 2; ++k) dst[m][k] = *(const PG8_LAS bf16x8*)(lds + PG8_SA(b, h) + aoff + m * 2048 + k * 1024); } while (0)
; #define PG8_MMA(ai, bj, At, Bt) do { __builtin_amdgcn_s_setprio(1); _Pragma("unroll") for (int m = 0; m < 4; ++m) _Pragma("unroll") for (int n = 0; n < 2; ++n) _Pragma("unroll") for (int k = 0; k < 2; ++k) \
;         acc[ai][bj][m][n] = __builtin_amdgcn_mfma_f32_16x16x32_bf16(Bt[n][k], At[m][k], acc[ai][bj][m][n], 0, 0, 0); __builtin_amdgcn_s_setprio(0); } while (0)
; #define PG8_WAIT_V(n) asm volatile("s_waitcnt vmcnt(" #n ")" ::: "memory")
; #define PG8_WAIT_L(n) asm volatile("s_waitcnt lgkmcnt(" #n ")" ::: "memory")
; #define PG8_BAR __builtin_amdgcn_s_barrier()
; #define PG8_SCHED __builtin_amdgcn_sched_barrier(0)
; template <class Epi, class Sched, bool ALIGN_EPI = false, bool SP2 = false>
; __device__ __forceinline__ void gemm_phase(PG8_LAS unsigned char* lds, const Gemm g, const Sched& S, const Epi& E, const int wid) {
;     ...
;             PG8_WAIT_V(8); PG8_WAIT_L(0); PG8_BAR; PG8_MMA(0, 0, At, B0); PG8_MMA(0, 1, At, B1); PG8_BAR; PG8_SCHED;
;             PG8_LDA(At, 0, 1); PG8_STAGE(PG8_SB(0, 0), b2, voffB); PG8_STAGE(PG8_SB(0, 1), b2 + hsB, voffB); PG8_STAGE(PG8_SA(0, 0), a2, voffA);
;             PG8_WAIT_V(8); PG8_WAIT_L(0); PG8_BAR; PG8_MMA(1, 0, At, B0); PG8_MMA(1, 1, At, B1); PG8_BAR; PG8_SCHED;
	s_waitcnt lgkmcnt(0)
	v_mfma_f32_16x16x32_bf16 v[126:129], v[130:133], v[174:177], v[126:129]
	v_mfma_f32_16x16x32_bf16 v[122:125], v[138:141], v[174:177], v[122:125]
	v_mfma_f32_16x16x32_bf16 v[118:121], v[130:133], v[190:193], v[118:121]
	v_mfma_f32_16x16x32_bf16 v[114:117], v[138:141], v[190:193], v[114:117]
	v_mfma_f32_16x16x32_bf16 v[106:109], v[130:133], v[198:201], v[106:109]
	v_mfma_f32_16x16x32_bf16 v[98:101], v[138:141], v[198:201], v[98:101]
	v_mfma_f32_16x16x32_bf16 v[90:93], v[130:133], v[206:209], v[90:93]
	v_mfma_f32_16x16x32_bf16 v[82:85], v[138:141], v[206:209], v[82:85]
	v_mfma_f32_16x16x32_bf16 v[126:129], v[134:137], v[178:181], v[126:129]
	v_mfma_f32_16x16x32_bf16 v[122:125], v[142:145], v[178:181], v[122:125]
	v_mfma_f32_16x16x32_bf16 v[118:121], v[134:137], v[194:197], v[118:121]
	v_mfma_f32_16x16x32_bf16 v[114:117], v[142:145], v[194:197], v[114:117]
	v_mfma_f32_16x16x32_bf16 v[106:109], v[134:137], v[202:205], v[106:109]
	v_mfma_f32_16x16x32_bf16 v[98:101], v[142:145], v[202:205], v[98:101]
	v_mfma_f32_16x16x32_bf16 v[90:93], v[134:137], v[210:213], v[90:93]
	v_mfma_f32_16x16x32_bf16 v[82:85], v[142:145], v[210:213], v[82:85]
	v_mfma_f32_16x16x32_bf16 v[110:113], v[146:149], v[174:177], v[110:113]
	v_mfma_f32_16x16x32_bf16 v[102:105], v[154:157], v[174:177], v[102:105]
	v_mfma_f32_16x16x32_bf16 v[94:97], v[146:149], v[190:193], v[94:97]
	v_mfma_f32_16x16x32_bf16 v[86:89], v[154:157], v[190:193], v[86:89]
	v_mfma_f32_16x16x32_bf16 v[78:81], v[146:149], v[198:201], v[78:81]
	v_mfma_f32_16x16x32_bf16 v[74:77], v[154:157], v[198:201], v[74:77]
	v_mfma_f32_16x16x32_bf16 v[70:73], v[146:149], v[206:209], v[70:73]
	v_mfma_f32_16x16x32_bf16 v[66:69], v[154:157], v[206:209], v[66:69]
	v_mfma_f32_16x16x32_bf16 v[110:113], v[150:153], v[178:181], v[110:113]
	v_mfma_f32_16x16x32_bf16 v[102:105], v[158:161], v[178:181], v[102:105]
	v_mfma_f32_16x16x32_bf16 v[94:97], v[150:153], v[194:197], v[94:97]
	v_mfma_f32_16x16x32_bf16 v[86:89], v[158:161], v[194:197], v[86:89]
	v_mfma_f32_16x16x32_bf16 v[78:81], v[150:153], v[202:205], v[78:81]
	v_mfma_f32_16x16x32_bf16 v[74:77], v[158:161], v[202:205], v[74:77]
	v_mfma_f32_16x16x32_bf16 v[70:73], v[150:153], v[210:213], v[70:73]
	v_mfma_f32_16x16x32_bf16 v[66:69], v[158:161], v[210:213], v[66:69]
	s_barrier
	s_add_i32 s8, s97, s28
	v_lshl_add_u64 v[182:183], s[70:71], 0, v[162:163]
	s_mov_b32 m0, s8
	ds_read_b128 v[174:177], v187 offset:16384
	ds_read_b128 v[178:181], v187 offset:17408
	ds_read_b128 v[190:193], v187 offset:18432
	ds_read_b128 v[194:197], v187 offset:19456
	ds_read_b128 v[198:201], v187 offset:20480
	ds_read_b128 v[202:205], v187 offset:21504
	ds_read_b128 v[206:209], v187 offset:22528
	ds_read_b128 v[210:213], v187 offset:23552
	global_load_lds_dwordx4 v[182:183], off
	s_add_i32 m0, s8, 0x2000
	s_add_u32 s24, s70, 0x100000
	v_lshl_add_u64 v[214:215], s[70:71], 0, v[164:165]
	s_addc_u32 s25, s71, 0
	s_add_i32 s8, s10, s28
	global_load_lds_dwordx4 v[214:215], off
	v_lshl_add_u64 v[216:217], s[24:25], 0, v[162:163]
	s_mov_b32 m0, s8
	v_lshl_add_u64 v[218:219], s[72:73], 0, v[164:165]
	global_load_lds_dwordx4 v[216:217], off
	v_lshl_add_u64 v[216:217], s[24:25], 0, v[164:165]
	s_add_i32 m0, s8, 0x2000
	s_nop 0
	global_load_lds_dwordx4 v[216:217], off
	v_lshl_add_u64 v[216:217], s[72:73], 0, v[162:163]
	s_mov_b32 m0, s85
	s_nop 0
	global_load_lds_dwordx4 v[216:217], off
	s_mov_b32 m0, s78
	s_nop 0
	global_load_lds_dwordx4 v[218:219], off
	s_waitcnt vmcnt(8)
	s_waitcnt lgkmcnt(0)
	s_barrier
	s_waitcnt lgkmcnt(0)
	v_mfma_f32_16x16x32_bf16 v[62:65], v[130:133], v[174:177], v[62:65]
	v_mfma_f32_16x16x32_bf16 v[58:61], v[138:141], v[174:177], v[58:61]
	v_mfma_f32_16x16x32_bf16 v[54:57], v[130:133], v[190:193], v[54:57]
	v_mfma_f32_16x16x32_bf16 v[50:53], v[138:141], v[190:193], v[50:53]
	v_mfma_f32_16x16x32_bf16 v[42:45], v[130:133], v[198:201], v[42:45]
	v_mfma_f32_16x16x32_bf16 v[34:37], v[138:141], v[198:201], v[34:37]
	v_mfma_f32_16x16x32_bf16 v[26:29], v[130:133], v[206:209], v[26:29]
	v_mfma_f32_16x16x32_bf16 v[18:21], v[138:141], v[206:209], v[18:21]
	v_mfma_f32_16x16x32_bf16 v[62:65], v[134:137], v[178:181], v[62:65]
	v_mfma_f32_16x16x32_bf16 v[58:61], v[142:145], v[178:181], v[58:61]
	v_mfma_f32_16x16x32_bf16 v[54:57], v[134:137], v[194:197], v[54:57]
	v_mfma_f32_16x16x32_bf16 v[50:53], v[142:145], v[194:197], v[50:53]
	v_mfma_f32_16x16x32_bf16 v[42:45], v[134:137], v[202:205], v[42:45]
	v_mfma_f32_16x16x32_bf16 v[34:37], v[142:145], v[202:205], v[34:37]
	v_mfma_f32_16x16x32_bf16 v[26:29], v[134:137], v[210:213], v[26:29]
	v_mfma_f32_16x16x32_bf16 v[18:21], v[142:145], v[210:213], v[18:21]
	v_mfma_f32_16x16x32_bf16 v[46:49], v[146:149], v[174:177], v[46:49]
	v_mfma_f32_16x16x32_bf16 v[38:41], v[154:157], v[174:177], v[38:41]
	v_mfma_f32_16x16x32_bf16 v[30:33], v[146:149], v[190:193], v[30:33]
	v_mfma_f32_16x16x32_bf16 v[22:25], v[154:157], v[190:193], v[22:25]
	v_mfma_f32_16x16x32_bf16 v[14:17], v[146:149], v[198:201], v[14:17]
	v_mfma_f32_16x16x32_bf16 v[10:13], v[154:157], v[198:201], v[10:13]
	v_mfma_f32_16x16x32_bf16 v[6:9], v[146:149], v[206:209], v[6:9]
	v_mfma_f32_16x16x32_bf16 v[2:5], v[154:157], v[206:209], v[2:5]
	v_mfma_f32_16x16x32_bf16 v[46:49], v[150:153], v[178:181], v[46:49]
	v_mfma_f32_16x16x32_bf16 v[38:41], v[158:161], v[178:181], v[38:41]
	v_mfma_f32_16x16x32_bf16 v[30:33], v[150:153], v[194:197], v[30:33]
	v_mfma_f32_16x16x32_bf16 v[22:25], v[158:161], v[194:197], v[22:25]
	v_mfma_f32_16x16x32_bf16 v[14:17], v[150:153], v[202:205], v[14:17]
	v_mfma_f32_16x16x32_bf16 v[10:13], v[158:161], v[202:205], v[10:13]
	v_mfma_f32_16x16x32_bf16 v[6:9], v[150:153], v[210:213], v[6:9]
	v_mfma_f32_16x16x32_bf16 v[2:5], v[158:161], v[210:213], v[2:5]
	s_barrier
; #define PG8_STAGE(bufoff, gbase, voff) do { _Pragma("unroll") for (int _i = 0; _i < 2; ++_i) \
;         __builtin_amdgcn_global_load_lds((const unsigned*)((const char*)(gbase) + (voff)[_i]), (PG8_LAS unsigned*)(lds + (bufoff) + ldsw + _i * 8192), 16, 0, 0); } while (0)
; #define PG8_LDA(dst, b, h) do { _Pragma("unroll") for (int m = 0; m < 4; ++m) _Pragma("unroll") for (int k = 0; k < 2; ++k) dst[m][k] = *(const PG8_LAS bf16x8*)(lds + PG8_SA(b, h) + aoff + m * 2048 + k * 1024); } while (0)
; #define PG8_LDB(dst, b, h) do { _Pragma("unroll") for (int n = 0; n < 2; ++n) _Pragma("unroll") for (int k = 0; k < 2; ++k) dst[n][k] = *(const PG8_LAS bf16x8*)(lds + PG8_SB(b, h) + boff + n * 2048 + k * 1024); } while (0)
; #define PG8_MMA(ai, bj, At, Bt) do { __builtin_amdgcn_s_setprio(1); _Pragma("unroll") for (int m = 0; m < 4; ++m) _Pragma("unroll") for (int n = 0; n < 2; ++n) _Pragma("unroll") for (int k = 0; k < 2; ++k) \
;         acc[ai][bj][m][n] = __builtin_amdgcn_mfma_f32_16x16x32_bf16(Bt[n][k], At[m][k], acc[ai][bj][m][n], 0, 0, 0); __builtin_amdgcn_s_setprio(0); } while (0)
; #define PG8_WAIT_V(n) asm volatile("s_waitcnt vmcnt(" #n ")" ::: "memory")
; #define PG8_WAIT_L(n) asm volatile("s_waitcnt lgkmcnt(" #n ")" ::: "memory")
; #define PG8_BAR __builtin_amdgcn_s_barrier()
; #define PG8_SCHED __builtin_amdgcn_sched_barrier(0)
; template <class Epi, class Sched, bool ALIGN_EPI = false, bool SP2 = false>
; __device__ __forceinline__ void gemm_phase(PG8_LAS unsigned char* lds, const Gemm g, const Sched& S, const Epi& E, const int wid) {
;     ...
;             PG8_LDB(B0, 1, 0); PG8_LDB(B1, 1, 1); PG8_SCHED; PG8_LDA(At, 1, 0); PG8_STAGE(PG8_SA(0, 1), a2 + hsA, voffA);
;             PG8_WAIT_V(8); PG8_WAIT_L(0); PG8_BAR; PG8_MMA(0, 0, At, B0); PG8_MMA(0, 1, At, B1); PG8_BAR; PG8_SCHED;
	s_add_i32 s8, 0, 0x18000
	s_add_i32 s9, 0, 0x1c000
	v_add_u32_e32 v142, s8, v184
	v_add_u32_e32 v158, s9, v184
	ds_read_b128 v[130:133], v142
	ds_read_b128 v[134:137], v142 offset:1024
	ds_read_b128 v[138:141], v142 offset:2048
	ds_read_b128 v[142:145], v142 offset:3072
	ds_read_b128 v[146:149], v158
	ds_read_b128 v[150:153], v158 offset:1024
	ds_read_b128 v[154:157], v158 offset:2048
	ds_read_b128 v[158:161], v158 offset:3072
	s_add_u32 s24, s72, 0x100000
	s_addc_u32 s25, s73, 0
	s_mov_b32 m0, s79
	v_lshl_add_u64 v[220:221], s[24:25], 0, v[162:163]
	ds_read_b128 v[174:177], v187 offset:32768
	ds_read_b128 v[178:181], v187 offset:33792
	ds_read_b128 v[190:193], v187 offset:34816
	ds_read_b128 v[194:197], v187 offset:35840
	ds_read_b128 v[198:201], v187 offset:36864
	ds_read_b128 v[202:205], v187 offset:37888
	ds_read_b128 v[206:209], v187 offset:38912
	ds_read_b128 v[210:213], v187 offset:39936
	global_load_lds_dwordx4 v[220:221], off
	v_lshl_add_u64 v[220:221], s[24:25], 0, v[164:165]
	s_mov_b32 m0, s80
	s_nop 0
	global_load_lds_dwordx4 v[220:221], off
	s_waitcnt vmcnt(8)
	s_waitcnt lgkmcnt(0)
	s_barrier
	s_waitcnt lgkmcnt(0)
	v_mfma_f32_16x16x32_bf16 v[126:129], v[130:133], v[174:177], v[126:129]
	v_mfma_f32_16x16x32_bf16 v[122:125], v[138:141], v[174:177], v[122:125]
	v_mfma_f32_16x16x32_bf16 v[118:121], v[130:133], v[190:193], v[118:121]
	v_mfma_f32_16x16x32_bf16 v[114:117], v[138:141], v[190:193], v[114:117]
	v_mfma_f32_16x16x32_bf16 v[106:109], v[130:133], v[198:201], v[106:109]
	v_mfma_f32_16x16x32_bf16 v[98:101], v[138:141], v[198:201], v[98:101]
	v_mfma_f32_16x16x32_bf16 v[90:93], v[130:133], v[206:209], v[90:93]
	v_mfma_f32_16x16x32_bf16 v[82:85], v[138:141], v[206:209], v[82:85]
	v_mfma_f32_16x16x32_bf16 v[126:129], v[134:137], v[178:181], v[126:129]
	v_mfma_f32_16x16x32_bf16 v[122:125], v[142:145], v[178:181], v[122:125]
	v_mfma_f32_16x16x32_bf16 v[118:121], v[134:137], v[194:197], v[118:121]
	v_mfma_f32_16x16x32_bf16 v[114:117], v[142:145], v[194:197], v[114:117]
	v_mfma_f32_16x16x32_bf16 v[106:109], v[134:137], v[202:205], v[106:109]
	v_mfma_f32_16x16x32_bf16 v[98:101], v[142:145], v[202:205], v[98:101]
	v_mfma_f32_16x16x32_bf16 v[90:93], v[134:137], v[210:213], v[90:93]
	v_mfma_f32_16x16x32_bf16 v[82:85], v[142:145], v[210:213], v[82:85]
	v_mfma_f32_16x16x32_bf16 v[110:113], v[146:149], v[174:177], v[110:113]
	v_mfma_f32_16x16x32_bf16 v[102:105], v[154:157], v[174:177], v[102:105]
	v_mfma_f32_16x16x32_bf16 v[94:97], v[146:149], v[190:193], v[94:97]
	v_mfma_f32_16x16x32_bf16 v[86:89], v[154:157], v[190:193], v[86:89]
	v_mfma_f32_16x16x32_bf16 v[78:81], v[146:149], v[198:201], v[78:81]
	v_mfma_f32_16x16x32_bf16 v[74:77], v[154:157], v[198:201], v[74:77]
	v_mfma_f32_16x16x32_bf16 v[70:73], v[146:149], v[206:209], v[70:73]
	v_mfma_f32_16x16x32_bf16 v[66:69], v[154:157], v[206:209], v[66:69]
	v_mfma_f32_16x16x32_bf16 v[110:113], v[150:153], v[178:181], v[110:113]
	v_mfma_f32_16x16x32_bf16 v[102:105], v[158:161], v[178:181], v[102:105]
	v_mfma_f32_16x16x32_bf16 v[94:97], v[150:153], v[194:197], v[94:97]
	v_mfma_f32_16x16x32_bf16 v[86:89], v[158:161], v[194:197], v[86:89]
	v_mfma_f32_16x16x32_bf16 v[78:81], v[150:153], v[202:205], v[78:81]
	v_mfma_f32_16x16x32_bf16 v[74:77], v[158:161], v[202:205], v[74:77]
	v_mfma_f32_16x16x32_bf16 v[70:73], v[150:153], v[210:213], v[70:73]
	v_mfma_f32_16x16x32_bf16 v[66:69], v[158:161], v[210:213], v[66:69]
	s_barrier
; #define PG8_STAGE(bufoff, gbase, voff) do { _Pragma("unroll") for (int _i = 0; _i < 2; ++_i) \
;         __builtin_amdgcn_global_load_lds((const unsigned*)((const char*)(gbase) + (voff)[_i]), (PG8_LAS unsigned*)(lds + (bufoff) + ldsw + _i * 8192), 16, 0, 0); } while (0)
; #define PG8_LDA(dst, b, h) do { _Pragma("unroll") for (int m = 0; m < 4; ++m) _Pragma("unroll") for (int k = 0; k < 2; ++k) dst[m][k] = *(const PG8_LAS bf16x8*)(lds + PG8_SA(b, h) + aoff + m * 2048 + k * 1024); } while (0)
; #define PG8_MMA(ai, bj, At, Bt) do { __builtin_amdgcn_s_setprio(1); _Pragma("unroll") for (int m = 0; m < 4; ++m) _Pragma("unroll") for (int n = 0; n < 2; ++n) _Pragma("unroll") for (int k = 0; k < 2; ++k) \
;         acc[ai][bj][m][n] = __builtin_amdgcn_mfma_f32_16x16x32_bf16(Bt[n][k], At[m][k], acc[ai][bj][m][n], 0, 0, 0); __builtin_amdgcn_s_setprio(0); } while (0)
; #define PG8_WAIT_V(n) asm volatile("s_waitcnt vmcnt(" #n ")" ::: "memory")
; #define PG8_WAIT_L(n) asm volatile("s_waitcnt lgkmcnt(" #n ")" ::: "memory")
; #define PG8_BAR __builtin_amdgcn_s_barrier()
; #define PG8_SCHED __builtin_amdgcn_sched_barrier(0)
; template <class Epi, class Sched, bool ALIGN_EPI = false, bool SP2 = false>
; __device__ __forceinline__ void gemm_phase(PG8_LAS unsigned char* lds, const Gemm g, const Sched& S, const Epi& E, const int wid) {
;     ...
;             PG8_LDA(At, 1, 1); PG8_STAGE(PG8_SB(1, 0), b3, voffB); PG8_STAGE(PG8_SB(1, 1), b3 + hsB, voffB); PG8_STAGE(PG8_SA(1, 0), a3, voffA);
;             PG8_WAIT_V(8); PG8_WAIT_L(0); PG8_BAR; PG8_MMA(1, 0, At, B0); PG8_MMA(1, 1, At, B1); PG8_BAR; PG8_SCHED;
;     ...
;         if constexpr (ALIGN_EPI) { if (wr == 0) PG8_BAR; }
	s_add_i32 s8, s8, s28
	v_lshl_add_u64 v[182:183], v[182:183], 0, s[46:47]
	s_mov_b32 m0, s8
	ds_read_b128 v[174:177], v187 offset:49152
	ds_read_b128 v[178:181], v187 offset:50176
	ds_read_b128 v[190:193], v187 offset:51200
	ds_read_b128 v[194:197], v187 offset:52224
	ds_read_b128 v[198:201], v187 offset:53248
	ds_read_b128 v[202:205], v187 offset:54272
	ds_read_b128 v[206:209], v187 offset:55296
	ds_read_b128 v[210:213], v187 offset:56320
	global_load_lds_dwordx4 v[182:183], off
	s_add_i32 m0, s8, 0x2000
	s_add_u32 s24, s70, 0x100080
	v_lshl_add_u64 v[182:183], v[214:215], 0, s[46:47]
	s_addc_u32 s25, s71, 0
	s_add_i32 s8, s9, s28
	global_load_lds_dwordx4 v[182:183], off
	v_lshl_add_u64 v[182:183], s[24:25], 0, v[162:163]
	s_mov_b32 m0, s8
	s_nop 0
	global_load_lds_dwordx4 v[182:183], off
	v_lshl_add_u64 v[182:183], s[24:25], 0, v[164:165]
	s_add_i32 m0, s8, 0x2000
	s_nop 0
	global_load_lds_dwordx4 v[182:183], off
	v_lshl_add_u64 v[182:183], v[216:217], 0, s[46:47]
	s_mov_b32 m0, s3
	s_nop 0
	global_load_lds_dwordx4 v[182:183], off
	v_lshl_add_u64 v[182:183], v[218:219], 0, s[46:47]
	s_mov_b32 m0, s87
	s_nop 0
	global_load_lds_dwordx4 v[182:183], off
	s_waitcnt vmcnt(8)
	s_waitcnt lgkmcnt(0)
	s_barrier
	s_waitcnt lgkmcnt(0)
	v_mfma_f32_16x16x32_bf16 v[62:65], v[130:133], v[174:177], v[62:65]
	v_mfma_f32_16x16x32_bf16 v[58:61], v[138:141], v[174:177], v[58:61]
	v_mfma_f32_16x16x32_bf16 v[54:57], v[130:133], v[190:193], v[54:57]
	v_mfma_f32_16x16x32_bf16 v[50:53], v[138:141], v[190:193], v[50:53]
	v_mfma_f32_16x16x32_bf16 v[42:45], v[130:133], v[198:201], v[42:45]
	v_mfma_f32_16x16x32_bf16 v[34:37], v[138:141], v[198:201], v[34:37]
	v_mfma_f32_16x16x32_bf16 v[26:29], v[130:133], v[206:209], v[26:29]
	v_mfma_f32_16x16x32_bf16 v[18:21], v[138:141], v[206:209], v[18:21]
	v_mfma_f32_16x16x32_bf16 v[62:65], v[134:137], v[178:181], v[62:65]
	v_mfma_f32_16x16x32_bf16 v[58:61], v[142:145], v[178:181], v[58:61]
	v_mfma_f32_16x16x32_bf16 v[54:57], v[134:137], v[194:197], v[54:57]
	v_mfma_f32_16x16x32_bf16 v[50:53], v[142:145], v[194:197], v[50:53]
	v_mfma_f32_16x16x32_bf16 v[42:45], v[134:137], v[202:205], v[42:45]
	v_mfma_f32_16x16x32_bf16 v[34:37], v[142:145], v[202:205], v[34:37]
	v_mfma_f32_16x16x32_bf16 v[26:29], v[134:137], v[210:213], v[26:29]
	v_mfma_f32_16x16x32_bf16 v[18:21], v[142:145], v[210:213], v[18:21]
	v_mfma_f32_16x16x32_bf16 v[46:49], v[146:149], v[174:177], v[46:49]
	v_mfma_f32_16x16x32_bf16 v[38:41], v[154:157], v[174:177], v[38:41]
	v_mfma_f32_16x16x32_bf16 v[30:33], v[146:149], v[190:193], v[30:33]
	v_mfma_f32_16x16x32_bf16 v[22:25], v[154:157], v[190:193], v[22:25]
	v_mfma_f32_16x16x32_bf16 v[14:17], v[146:149], v[198:201], v[14:17]
	v_mfma_f32_16x16x32_bf16 v[10:13], v[154:157], v[198:201], v[10:13]
	v_mfma_f32_16x16x32_bf16 v[6:9], v[146:149], v[206:209], v[6:9]
	v_mfma_f32_16x16x32_bf16 v[2:5], v[154:157], v[206:209], v[2:5]
	v_mfma_f32_16x16x32_bf16 v[46:49], v[150:153], v[178:181], v[46:49]
	v_mfma_f32_16x16x32_bf16 v[38:41], v[158:161], v[178:181], v[38:41]
	v_mfma_f32_16x16x32_bf16 v[30:33], v[150:153], v[194:197], v[30:33]
	v_mfma_f32_16x16x32_bf16 v[22:25], v[158:161], v[194:197], v[22:25]
	v_mfma_f32_16x16x32_bf16 v[14:17], v[150:153], v[202:205], v[14:17]
	v_mfma_f32_16x16x32_bf16 v[10:13], v[158:161], v[202:205], v[10:13]
	v_mfma_f32_16x16x32_bf16 v[6:9], v[150:153], v[210:213], v[6:9]
	v_mfma_f32_16x16x32_bf16 v[2:5], v[158:161], v[210:213], v[2:5]
	s_barrier
	s_add_u32 s12, s12, 0x100
	s_addc_u32 s13, s13, 0
	s_add_u32 s75, s75, 0x100
	s_addc_u32 vcc_lo, vcc_lo, 0
	s_cmp_ge_u32 vcc_hi, s69
	s_mov_b32 s72, vcc_hi
	s_cbranch_scc0 .LBB0_1599
	s_setprio 0
	s_and_b64 vcc, exec, s[6:7]
	s_cbranch_vccz .LBB0_1602
	s_barrier
